# RWKV scan: operands pre-scaled by in-chunk decay product in the converter waves (one operand vector and two packed FMAs fewer per step), single LDS wait per step, paired v reads; conversion split over
# speedup vs baseline: 1.0266x; 1.0266x over previous
; #define GAS __attribute__((address_space(1)))
; __device__ __forceinline__ int mk_tid(int wid_s) { int t = wid_s * 64 + (int)__builtin_amdgcn_mbcnt_hi(~0u, __builtin_amdgcn_mbcnt_lo(~0u, 0u)); asm volatile("" : "+v"(t)); return t; }
; template <int MODE>
; __device__ __forceinline__ void rwkv_scan_unit(int wid_s, const bf16* SIbh_, bf16* Yb_, int ystride, int quarter, float* ldsf) {
;     const int tid_ = mk_tid(wid_s);
;     const GAS bf16* SIbh = (const GAS bf16*)SIbh_; GAS bf16* Yb = (GAS bf16*)Yb_;
;     const int tid = tid_, lane = tid & 63, wv = tid >> 6, hw = wv - 4;
;     float* PYb = ldsf + 4 * (16 * 384);
;     u32x4 hreg[12];
;     if (wv >= 4 && wv < 7) {
; #pragma unroll
;         for (int i = 0; i < 12; ++i) hreg[i] = *(const GAS u32x4*)(SIbh + (size_t)hw * (16 * 384) + (size_t)(lane + 64 * i) * 8);
;     }
;     f32x2 Sa = {0.f, 0.f}, Sb = {0.f, 0.f};
;     const int rowl = quarter * 16 + (wv & 3) * 4 + (lane >> 4), c4 = (lane & 15) * 4;
;     __syncthreads();
;     ...
;     if (wv == 4) SCAN_CONVERT(0);
.LBB0_1393:
	s_andn2_b64 vcc, exec, s[2:3]
	s_cbranch_vccnz .LBB0_1416
	v_readlane_b32 s4, v254, 2
	v_readlane_b32 s6, v254, 4
	v_readlane_b32 s7, v254, 5
	s_mov_b64 s[2:3], s[6:7]
	v_readlane_b32 s0, v254, 31
	s_add_u32 s0, s2, s0
	v_readlane_b32 s2, v254, 30
	v_mov_b32_e32 v53, v169
	s_addc_u32 s2, s3, s2
	s_add_u32 s6, s0, 0xae00000
	v_ashrrev_i32_e32 v54, 6, v53
	v_and_b32_e32 v52, 63, v53
	v_add_u32_e32 v56, -4, v54
	s_addc_u32 s7, s2, 0
	v_cmp_gt_u32_e32 vcc, 3, v56
	v_lshlrev_b32_e32 v48, 4, v52
	v_readlane_b32 s5, v254, 3
	s_and_saveexec_b64 s[2:3], vcc
	s_cbranch_execz .LBB0_1396
	s_movk_i32 s0, 0x3000
	v_mul_lo_u32 v64, v56, s0
	v_lshrrev_b32_e32 v66, 5, v52
	v_mul_u32_u24_e32 v66, 0x1800, v66
	v_and_b32_e32 v67, 31, v52
	v_lshl_add_u32 v67, v67, 2, v64
	v_add_u32_e32 v64, v67, v66
	v_mov_b32_e32 v65, 0
	v_mov_b32_e32 v66, v67
	v_mov_b32_e32 v67, 0
	v_lshl_add_u64 v[64:65], s[6:7], 0, v[64:65]
	v_lshl_add_u64 v[66:67], s[6:7], 0, v[66:67]
	s_movk_i32 s12, 0xf00
	s_mov_b32 s13, 0
	v_lshl_add_u64 v[68:69], v[64:65], 0, s[12:13]
	v_lshl_add_u64 v[70:71], v[66:67], 0, s[12:13]
	global_load_dword v0, v[64:65], off
	global_load_dword v1, v[64:65], off offset:128
	global_load_dword v2, v[64:65], off offset:256
	global_load_dword v3, v[64:65], off offset:384
	global_load_dword v4, v[64:65], off offset:512
	global_load_dword v5, v[64:65], off offset:640
	global_load_dword v6, v[64:65], off offset:768
	global_load_dword v7, v[64:65], off offset:896
	global_load_dword v8, v[64:65], off offset:1024
	global_load_dword v9, v[64:65], off offset:1152
	global_load_dword v10, v[64:65], off offset:1280
	global_load_dword v11, v[64:65], off offset:1408
	global_load_dword v12, v[64:65], off offset:1536
	global_load_dword v13, v[64:65], off offset:1664
	global_load_dword v14, v[64:65], off offset:1792
	global_load_dword v15, v[64:65], off offset:1920
	global_load_dword v16, v[64:65], off offset:2048
	global_load_dword v17, v[64:65], off offset:2176
	global_load_dword v18, v[64:65], off offset:2304
	global_load_dword v19, v[64:65], off offset:2432
	global_load_dword v20, v[64:65], off offset:2560
	global_load_dword v21, v[64:65], off offset:2688
	global_load_dword v22, v[64:65], off offset:2816
	global_load_dword v23, v[64:65], off offset:2944
	global_load_dword v24, v[64:65], off offset:3072
	global_load_dword v25, v[64:65], off offset:3200
	global_load_dword v26, v[64:65], off offset:3328
	global_load_dword v27, v[64:65], off offset:3456
	global_load_dword v28, v[64:65], off offset:3584
	global_load_dword v29, v[64:65], off offset:3712
	global_load_dword v30, v[64:65], off offset:3840
	global_load_dword v31, v[64:65], off offset:3968
	global_load_dword v32, v[68:69], off offset:256
	global_load_dword v33, v[68:69], off offset:384
	global_load_dword v34, v[68:69], off offset:512
	global_load_dword v35, v[68:69], off offset:640
	global_load_dword v36, v[68:69], off offset:768
	global_load_dword v37, v[68:69], off offset:896
	global_load_dword v38, v[68:69], off offset:1024
	global_load_dword v39, v[68:69], off offset:1152
	global_load_dword v40, v[68:69], off offset:1280
	global_load_dword v41, v[68:69], off offset:1408
	global_load_dword v42, v[68:69], off offset:1536
	global_load_dword v43, v[68:69], off offset:1664
	global_load_dword v44, v[68:69], off offset:1792
	global_load_dword v45, v[68:69], off offset:1920
	global_load_dword v46, v[68:69], off offset:2048
	global_load_dword v47, v[68:69], off offset:2176
	global_load_dword v80, v[66:67], off offset:128
	global_load_dword v81, v[66:67], off offset:896
	global_load_dword v82, v[66:67], off offset:1664
	global_load_dword v83, v[66:67], off offset:2432
	global_load_dword v84, v[66:67], off offset:3200
	global_load_dword v85, v[66:67], off offset:3968
	global_load_dword v86, v[70:71], off offset:896
	global_load_dword v87, v[70:71], off offset:1664
.LBB0_1396:
	s_or_b64 exec, exec, s[2:3]
	v_cmp_ne_u32_e32 vcc, 4, v54
	v_lshrrev_b32_e32 v144, 5, v52
	v_mul_u32_u24_e32 v144, 0xc00, v144
	v_and_b32_e32 v49, 31, v52
	v_lshl_add_u32 v144, v49, 1, v144
	s_waitcnt vmcnt(0) lgkmcnt(0)
	s_barrier
	s_and_saveexec_b64 s[2:3], vcc
	s_xor_b64 s[2:3], exec, s[2:3]
	v_mov_b64_e32 v[50:51], v[144:145]
	s_or_saveexec_b64 s[2:3], s[2:3]
	v_lshlrev_b32_e32 v49, 5, v52
	v_add_u32_e32 v57, 0, v49
	s_xor_b64 exec, exec, s[2:3]
	s_cbranch_execz .LBB0_1400
; __device__ __forceinline__ float allreduce16(float x) { x += dppf<0xB1>(x); x += dppf<0x4E>(x); x += dppf<0x141>(x); x += dppf<0x140>(x); return x; }
; template <int MODE>
; __device__ __forceinline__ void rwkv_scan_unit(int wid_s, const bf16* SIbh_, bf16* Yb_, int ystride, int quarter, float* ldsf) {
;     ...
;     if (wv == 4) SCAN_CONVERT(0);
;     ...
;                 for (int s = 0; s < 16; ++s) {
;                     const float* qn = B + ((MODE & 2) ? 0 : ((s + 1) & 15)) * 384;
;                     const f32x4 nr4 = *(const f32x4*)(qn + c4), nom4 = *(const f32x4*)(qn + 64 + c4), nk4 = *(const f32x4*)(qn + 128 + c4), nkk4 = *(const f32x4*)(qn + 192 + c4), nka4 = *(const f32x4*)(qn + 256 + c4);
;                     const float nv = qn[320 + rowl];
;                     const f32x2 pa = Sa * (f32x2){kk4.x, kk4.y} + Sb * (f32x2){kk4.z, kk4.w};
;                     const float sa = (MODE & 1) ? (pa.x + pa.y) : allreduce16(pa.x + pa.y);
;                     Sa = Sa - Sa * (f32x2){om4.x, om4.y} + (f32x2){k4.x, k4.y} * v; Sb = Sb - Sb * (f32x2){om4.z, om4.w} + (f32x2){k4.z, k4.w} * v;
;                     Sa = Sa - (f32x2){ka4.x, ka4.y} * sa; Sb = Sb - (f32x2){ka4.z, ka4.w} * sa;
	v_mov_b32_e32 v98, 1.0
	v_lshrrev_b32_e32 v63, 10, v57
	v_mul_u32_u24_e32 v63, 0x3000, v63
	v_bfe_u32 v99, v57, 5, 5
	v_lshl_add_u32 v63, v99, 3, v63
	v_mov_b32_e32 v72, 1.0
	v_mov_b32_e32 v73, 1.0
	v_lshlrev_b32_e32 v78, 16, v80
	v_and_b32_e32 v79, 0xffff0000, v80
	v_sub_f32_e32 v78, 1.0, v78
	v_sub_f32_e32 v79, 1.0, v79
	v_mul_f32_e32 v72, v72, v78
	v_mul_f32_e32 v73, v73, v79
	v_lshlrev_b32_e32 v78, 16, v81
	v_and_b32_e32 v79, 0xffff0000, v81
	v_sub_f32_e32 v78, 1.0, v78
	v_sub_f32_e32 v79, 1.0, v79
	v_mul_f32_e32 v72, v72, v78
	v_mul_f32_e32 v73, v73, v79
	v_lshlrev_b32_e32 v78, 16, v82
	v_and_b32_e32 v79, 0xffff0000, v82
	v_sub_f32_e32 v78, 1.0, v78
	v_sub_f32_e32 v79, 1.0, v79
	v_mul_f32_e32 v72, v72, v78
	v_mul_f32_e32 v73, v73, v79
	v_lshlrev_b32_e32 v78, 16, v83
	v_and_b32_e32 v79, 0xffff0000, v83
	v_sub_f32_e32 v78, 1.0, v78
	v_sub_f32_e32 v79, 1.0, v79
	v_mul_f32_e32 v72, v72, v78
	v_mul_f32_e32 v73, v73, v79
	v_lshlrev_b32_e32 v78, 16, v84
	v_and_b32_e32 v79, 0xffff0000, v84
	v_sub_f32_e32 v78, 1.0, v78
	v_sub_f32_e32 v79, 1.0, v79
	v_mul_f32_e32 v72, v72, v78
	v_mul_f32_e32 v73, v73, v79
	v_lshlrev_b32_e32 v78, 16, v85
	v_and_b32_e32 v79, 0xffff0000, v85
	v_sub_f32_e32 v78, 1.0, v78
	v_sub_f32_e32 v79, 1.0, v79
	v_mul_f32_e32 v72, v72, v78
	v_mul_f32_e32 v73, v73, v79
	v_lshlrev_b32_e32 v78, 16, v86
	v_and_b32_e32 v79, 0xffff0000, v86
	v_sub_f32_e32 v78, 1.0, v78
	v_sub_f32_e32 v79, 1.0, v79
	v_mul_f32_e32 v72, v72, v78
	v_mul_f32_e32 v73, v73, v79
	v_lshlrev_b32_e32 v78, 16, v87
	v_and_b32_e32 v79, 0xffff0000, v87
	v_sub_f32_e32 v78, 1.0, v78
	v_sub_f32_e32 v79, 1.0, v79
	v_mul_f32_e32 v72, v72, v78
	v_mul_f32_e32 v73, v73, v79
	v_cmp_gt_u32_e32 vcc, 0x400, v57
	s_nop 1
	v_cndmask_b32_e32 v72, v72, v98, vcc
	v_cndmask_b32_e32 v73, v73, v98, vcc
	v_lshlrev_b32_e32 v78, 16, v1
	v_and_b32_e32 v79, 0xffff0000, v1
	v_sub_f32_e32 v78, 1.0, v78
	v_sub_f32_e32 v79, 1.0, v79
	v_mul_f32_e32 v74, v72, v78
	v_mul_f32_e32 v75, v73, v79
	v_lshlrev_b32_e32 v88, 16, v3
	v_and_b32_e32 v89, 0xffff0000, v3
	v_rcp_f32_e32 v76, v74
	v_rcp_f32_e32 v77, v75
	v_mul_f32_e32 v88, v88, v72
	v_mul_f32_e32 v89, v89, v73
	v_lshlrev_b32_e32 v90, 16, v0
	v_and_b32_e32 v91, 0xffff0000, v0
	v_mul_f32_e32 v90, v90, v74
	v_mul_f32_e32 v91, v91, v75
	v_lshlrev_b32_e32 v92, 16, v2
	v_and_b32_e32 v93, 0xffff0000, v2
	v_mul_f32_e32 v92, v92, v76
	v_mul_f32_e32 v93, v93, v77
	v_lshlrev_b32_e32 v94, 16, v4
	v_and_b32_e32 v95, 0xffff0000, v4
	v_mul_f32_e32 v94, v94, v76
	v_mul_f32_e32 v95, v95, v77
	v_lshlrev_b32_e32 v96, 16, v5
	v_and_b32_e32 v97, 0xffff0000, v5
	ds_write_b64 v63, v[90:91]
	ds_write_b64 v63, v[74:75] offset:256
	ds_write_b64 v63, v[92:93] offset:512
	ds_write_b64 v63, v[88:89] offset:768
	ds_write_b64 v63, v[94:95] offset:1024
	ds_write_b64 v63, v[96:97] offset:1280
	v_mov_b32_e32 v72, v74
	v_mov_b32_e32 v73, v75
	v_lshlrev_b32_e32 v78, 16, v7
	v_and_b32_e32 v79, 0xffff0000, v7
	v_sub_f32_e32 v78, 1.0, v78
	v_sub_f32_e32 v79, 1.0, v79
	v_mul_f32_e32 v74, v72, v78
	v_mul_f32_e32 v75, v73, v79
	v_lshlrev_b32_e32 v88, 16, v9
	v_and_b32_e32 v89, 0xffff0000, v9
	v_rcp_f32_e32 v76, v74
	v_rcp_f32_e32 v77, v75
	v_mul_f32_e32 v88, v88, v72
	v_mul_f32_e32 v89, v89, v73
	v_lshlrev_b32_e32 v90, 16, v6
	v_and_b32_e32 v91, 0xffff0000, v6
	v_mul_f32_e32 v90, v90, v74
	v_mul_f32_e32 v91, v91, v75
	v_lshlrev_b32_e32 v92, 16, v8
	v_and_b32_e32 v93, 0xffff0000, v8
	v_mul_f32_e32 v92, v92, v76
	v_mul_f32_e32 v93, v93, v77
	v_lshlrev_b32_e32 v94, 16, v10
	v_and_b32_e32 v95, 0xffff0000, v10
	v_mul_f32_e32 v94, v94, v76
	v_mul_f32_e32 v95, v95, v77
	v_lshlrev_b32_e32 v96, 16, v11
	v_and_b32_e32 v97, 0xffff0000, v11
	ds_write_b64 v63, v[90:91] offset:1536
	ds_write_b64 v63, v[74:75] offset:1792
	ds_write_b64 v63, v[92:93] offset:2048
	ds_write_b64 v63, v[88:89] offset:2304
	ds_write_b64 v63, v[94:95] offset:2560
	ds_write_b64 v63, v[96:97] offset:2816
	v_mov_b32_e32 v72, v74
	v_mov_b32_e32 v73, v75
	v_lshlrev_b32_e32 v78, 16, v13
	v_and_b32_e32 v79, 0xffff0000, v13
	v_sub_f32_e32 v78, 1.0, v78
	v_sub_f32_e32 v79, 1.0, v79
	v_mul_f32_e32 v74, v72, v78
	v_mul_f32_e32 v75, v73, v79
	v_lshlrev_b32_e32 v88, 16, v15
	v_and_b32_e32 v89, 0xffff0000, v15
	v_rcp_f32_e32 v76, v74
	v_rcp_f32_e32 v77, v75
	v_mul_f32_e32 v88, v88, v72
	v_mul_f32_e32 v89, v89, v73
	v_lshlrev_b32_e32 v90, 16, v12
	v_and_b32_e32 v91, 0xffff0000, v12
	v_mul_f32_e32 v90, v90, v74
	v_mul_f32_e32 v91, v91, v75
	v_lshlrev_b32_e32 v92, 16, v14
	v_and_b32_e32 v93, 0xffff0000, v14
	v_mul_f32_e32 v92, v92, v76
	v_mul_f32_e32 v93, v93, v77
	v_lshlrev_b32_e32 v94, 16, v16
	v_and_b32_e32 v95, 0xffff0000, v16
	v_mul_f32_e32 v94, v94, v76
	v_mul_f32_e32 v95, v95, v77
	v_lshlrev_b32_e32 v96, 16, v17
	v_and_b32_e32 v97, 0xffff0000, v17
	ds_write_b64 v63, v[90:91] offset:3072
	ds_write_b64 v63, v[74:75] offset:3328
	ds_write_b64 v63, v[92:93] offset:3584
	ds_write_b64 v63, v[88:89] offset:3840
	ds_write_b64 v63, v[94:95] offset:4096
	ds_write_b64 v63, v[96:97] offset:4352
	v_mov_b32_e32 v72, v74
	v_mov_b32_e32 v73, v75
	v_lshlrev_b32_e32 v78, 16, v19
	v_and_b32_e32 v79, 0xffff0000, v19
	v_sub_f32_e32 v78, 1.0, v78
	v_sub_f32_e32 v79, 1.0, v79
	v_mul_f32_e32 v74, v72, v78
	v_mul_f32_e32 v75, v73, v79
	v_lshlrev_b32_e32 v88, 16, v21
	v_and_b32_e32 v89, 0xffff0000, v21
	v_rcp_f32_e32 v76, v74
	v_rcp_f32_e32 v77, v75
	v_mul_f32_e32 v88, v88, v72
	v_mul_f32_e32 v89, v89, v73
	v_lshlrev_b32_e32 v90, 16, v18
	v_and_b32_e32 v91, 0xffff0000, v18
	v_mul_f32_e32 v90, v90, v74
	v_mul_f32_e32 v91, v91, v75
	v_lshlrev_b32_e32 v92, 16, v20
	v_and_b32_e32 v93, 0xffff0000, v20
	v_mul_f32_e32 v92, v92, v76
	v_mul_f32_e32 v93, v93, v77
	v_lshlrev_b32_e32 v94, 16, v22
	v_and_b32_e32 v95, 0xffff0000, v22
	v_mul_f32_e32 v94, v94, v76
	v_mul_f32_e32 v95, v95, v77
	v_lshlrev_b32_e32 v96, 16, v23
	v_and_b32_e32 v97, 0xffff0000, v23
	ds_write_b64 v63, v[90:91] offset:4608
	ds_write_b64 v63, v[74:75] offset:4864
	ds_write_b64 v63, v[92:93] offset:5120
	ds_write_b64 v63, v[88:89] offset:5376
	ds_write_b64 v63, v[94:95] offset:5632
	ds_write_b64 v63, v[96:97] offset:5888
	v_mov_b32_e32 v72, v74
	v_mov_b32_e32 v73, v75
	v_lshlrev_b32_e32 v78, 16, v25
	v_and_b32_e32 v79, 0xffff0000, v25
	v_sub_f32_e32 v78, 1.0, v78
	v_sub_f32_e32 v79, 1.0, v79
	v_mul_f32_e32 v74, v72, v78
	v_mul_f32_e32 v75, v73, v79
	v_lshlrev_b32_e32 v88, 16, v27
	v_and_b32_e32 v89, 0xffff0000, v27
	v_rcp_f32_e32 v76, v74
	v_rcp_f32_e32 v77, v75
	v_mul_f32_e32 v88, v88, v72
	v_mul_f32_e32 v89, v89, v73
	v_lshlrev_b32_e32 v90, 16, v24
	v_and_b32_e32 v91, 0xffff0000, v24
	v_mul_f32_e32 v90, v90, v74
	v_mul_f32_e32 v91, v91, v75
	v_lshlrev_b32_e32 v92, 16, v26
	v_and_b32_e32 v93, 0xffff0000, v26
	v_mul_f32_e32 v92, v92, v76
	v_mul_f32_e32 v93, v93, v77
	v_lshlrev_b32_e32 v94, 16, v28
	v_and_b32_e32 v95, 0xffff0000, v28
	v_mul_f32_e32 v94, v94, v76
	v_mul_f32_e32 v95, v95, v77
	v_lshlrev_b32_e32 v96, 16, v29
	v_and_b32_e32 v97, 0xffff0000, v29
	ds_write_b64 v63, v[90:91] offset:6144
	ds_write_b64 v63, v[74:75] offset:6400
	ds_write_b64 v63, v[92:93] offset:6656
	ds_write_b64 v63, v[88:89] offset:6912
	ds_write_b64 v63, v[94:95] offset:7168
	ds_write_b64 v63, v[96:97] offset:7424
	v_mov_b32_e32 v72, v74
	v_mov_b32_e32 v73, v75
	v_lshlrev_b32_e32 v78, 16, v31
	v_and_b32_e32 v79, 0xffff0000, v31
	v_sub_f32_e32 v78, 1.0, v78
	v_sub_f32_e32 v79, 1.0, v79
	v_mul_f32_e32 v74, v72, v78
	v_mul_f32_e32 v75, v73, v79
	v_lshlrev_b32_e32 v88, 16, v33
	v_and_b32_e32 v89, 0xffff0000, v33
	v_rcp_f32_e32 v76, v74
	v_rcp_f32_e32 v77, v75
	v_mul_f32_e32 v88, v88, v72
	v_mul_f32_e32 v89, v89, v73
	v_lshlrev_b32_e32 v90, 16, v30
	v_and_b32_e32 v91, 0xffff0000, v30
	v_mul_f32_e32 v90, v90, v74
	v_mul_f32_e32 v91, v91, v75
	v_lshlrev_b32_e32 v92, 16, v32
	v_and_b32_e32 v93, 0xffff0000, v32
	v_mul_f32_e32 v92, v92, v76
	v_mul_f32_e32 v93, v93, v77
	v_lshlrev_b32_e32 v94, 16, v34
	v_and_b32_e32 v95, 0xffff0000, v34
	v_mul_f32_e32 v94, v94, v76
	v_mul_f32_e32 v95, v95, v77
	v_lshlrev_b32_e32 v96, 16, v35
	v_and_b32_e32 v97, 0xffff0000, v35
	ds_write_b64 v63, v[90:91] offset:7680
	ds_write_b64 v63, v[74:75] offset:7936
	ds_write_b64 v63, v[92:93] offset:8192
	ds_write_b64 v63, v[88:89] offset:8448
	ds_write_b64 v63, v[94:95] offset:8704
	ds_write_b64 v63, v[96:97] offset:8960
	v_mov_b32_e32 v72, v74
	v_mov_b32_e32 v73, v75
	v_lshlrev_b32_e32 v78, 16, v37
	v_and_b32_e32 v79, 0xffff0000, v37
	v_sub_f32_e32 v78, 1.0, v78
	v_sub_f32_e32 v79, 1.0, v79
	v_mul_f32_e32 v74, v72, v78
	v_mul_f32_e32 v75, v73, v79
	v_lshlrev_b32_e32 v88, 16, v39
	v_and_b32_e32 v89, 0xffff0000, v39
	v_rcp_f32_e32 v76, v74
	v_rcp_f32_e32 v77, v75
	v_mul_f32_e32 v88, v88, v72
	v_mul_f32_e32 v89, v89, v73
	v_lshlrev_b32_e32 v90, 16, v36
	v_and_b32_e32 v91, 0xffff0000, v36
	v_mul_f32_e32 v90, v90, v74
	v_mul_f32_e32 v91, v91, v75
	v_lshlrev_b32_e32 v92, 16, v38
	v_and_b32_e32 v93, 0xffff0000, v38
	v_mul_f32_e32 v92, v92, v76
	v_mul_f32_e32 v93, v93, v77
	v_lshlrev_b32_e32 v94, 16, v40
	v_and_b32_e32 v95, 0xffff0000, v40
	v_mul_f32_e32 v94, v94, v76
	v_mul_f32_e32 v95, v95, v77
	v_lshlrev_b32_e32 v96, 16, v41
	v_and_b32_e32 v97, 0xffff0000, v41
	ds_write_b64 v63, v[90:91] offset:9216
	ds_write_b64 v63, v[74:75] offset:9472
	ds_write_b64 v63, v[92:93] offset:9728
	ds_write_b64 v63, v[88:89] offset:9984
	ds_write_b64 v63, v[94:95] offset:10240
	ds_write_b64 v63, v[96:97] offset:10496
	v_mov_b32_e32 v72, v74
	v_mov_b32_e32 v73, v75
	v_lshlrev_b32_e32 v78, 16, v43
	v_and_b32_e32 v79, 0xffff0000, v43
	v_sub_f32_e32 v78, 1.0, v78
	v_sub_f32_e32 v79, 1.0, v79
	v_mul_f32_e32 v74, v72, v78
	v_mul_f32_e32 v75, v73, v79
	v_lshlrev_b32_e32 v88, 16, v45
	v_and_b32_e32 v89, 0xffff0000, v45
	v_rcp_f32_e32 v76, v74
	v_rcp_f32_e32 v77, v75
	v_mul_f32_e32 v88, v88, v72
	v_mul_f32_e32 v89, v89, v73
; template <int MODE>
; __device__ __forceinline__ void rwkv_scan_unit(int wid_s, const bf16* SIbh_, bf16* Yb_, int ystride, int quarter, float* ldsf) {
;     ...
;     if (wv == 4) SCAN_CONVERT(0);
	v_lshlrev_b32_e32 v90, 16, v42
	v_and_b32_e32 v91, 0xffff0000, v42
	v_mul_f32_e32 v90, v90, v74
	v_mul_f32_e32 v91, v91, v75
	v_lshlrev_b32_e32 v92, 16, v44
	v_and_b32_e32 v93, 0xffff0000, v44
	v_mul_f32_e32 v92, v92, v76
	v_mul_f32_e32 v93, v93, v77
	v_lshlrev_b32_e32 v94, 16, v46
	v_and_b32_e32 v95, 0xffff0000, v46
	v_mul_f32_e32 v94, v94, v76
	v_mul_f32_e32 v95, v95, v77
	v_lshlrev_b32_e32 v96, 16, v47
	v_and_b32_e32 v97, 0xffff0000, v47
	ds_write_b64 v63, v[90:91] offset:10752
	ds_write_b64 v63, v[74:75] offset:11008
	ds_write_b64 v63, v[92:93] offset:11264
	ds_write_b64 v63, v[88:89] offset:11520
	ds_write_b64 v63, v[94:95] offset:11776
	ds_write_b64 v63, v[96:97] offset:12032
	v_mov_b32_e32 v72, v74
	v_mov_b32_e32 v73, v75
	v_lshrrev_b32_e32 v66, 5, v52
	v_mul_u32_u24_e32 v66, 0x1800, v66
	v_and_b32_e32 v67, 31, v52
	v_lshlrev_b32_e32 v67, 2, v67
	v_add_u32_e32 v64, v67, v66
	v_mov_b32_e32 v65, 0
	v_mov_b32_e32 v66, v67
	v_mov_b32_e32 v67, 0
	s_mov_b64 s[12:13], 0x9000
	v_lshl_add_u64 v[64:65], s[6:7], 0, v[64:65]
	v_lshl_add_u64 v[66:67], s[6:7], 0, v[66:67]
	v_lshl_add_u64 v[64:65], v[64:65], 0, s[12:13]
	v_lshl_add_u64 v[66:67], v[66:67], 0, s[12:13]
	s_movk_i32 s12, 0xf00
	s_mov_b32 s13, 0
	v_lshl_add_u64 v[68:69], v[64:65], 0, s[12:13]
	v_lshl_add_u64 v[70:71], v[66:67], 0, s[12:13]
	global_load_dword v0, v[64:65], off
	global_load_dword v1, v[64:65], off offset:128
	global_load_dword v2, v[64:65], off offset:256
	global_load_dword v3, v[64:65], off offset:384
	global_load_dword v4, v[64:65], off offset:512
	global_load_dword v5, v[64:65], off offset:640
	global_load_dword v6, v[64:65], off offset:768
	global_load_dword v7, v[64:65], off offset:896
	global_load_dword v8, v[64:65], off offset:1024
	global_load_dword v9, v[64:65], off offset:1152
	global_load_dword v10, v[64:65], off offset:1280
	global_load_dword v11, v[64:65], off offset:1408
	global_load_dword v12, v[64:65], off offset:1536
	global_load_dword v13, v[64:65], off offset:1664
	global_load_dword v14, v[64:65], off offset:1792
	global_load_dword v15, v[64:65], off offset:1920
	global_load_dword v16, v[64:65], off offset:2048
	global_load_dword v17, v[64:65], off offset:2176
	global_load_dword v18, v[64:65], off offset:2304
	global_load_dword v19, v[64:65], off offset:2432
	global_load_dword v20, v[64:65], off offset:2560
	global_load_dword v21, v[64:65], off offset:2688
	global_load_dword v22, v[64:65], off offset:2816
	global_load_dword v23, v[64:65], off offset:2944
	global_load_dword v24, v[64:65], off offset:3072
	global_load_dword v25, v[64:65], off offset:3200
	global_load_dword v26, v[64:65], off offset:3328
	global_load_dword v27, v[64:65], off offset:3456
	global_load_dword v28, v[64:65], off offset:3584
	global_load_dword v29, v[64:65], off offset:3712
	global_load_dword v30, v[64:65], off offset:3840
	global_load_dword v31, v[64:65], off offset:3968
	global_load_dword v32, v[68:69], off offset:256
	global_load_dword v33, v[68:69], off offset:384
	global_load_dword v34, v[68:69], off offset:512
	global_load_dword v35, v[68:69], off offset:640
	global_load_dword v36, v[68:69], off offset:768
	global_load_dword v37, v[68:69], off offset:896
	global_load_dword v38, v[68:69], off offset:1024
	global_load_dword v39, v[68:69], off offset:1152
	global_load_dword v40, v[68:69], off offset:1280
	global_load_dword v41, v[68:69], off offset:1408
	global_load_dword v42, v[68:69], off offset:1536
	global_load_dword v43, v[68:69], off offset:1664
	global_load_dword v44, v[68:69], off offset:1792
	global_load_dword v45, v[68:69], off offset:1920
	global_load_dword v46, v[68:69], off offset:2048
	global_load_dword v47, v[68:69], off offset:2176
	global_load_dword v80, v[66:67], off offset:128
	global_load_dword v81, v[66:67], off offset:896
	global_load_dword v82, v[66:67], off offset:1664
	global_load_dword v83, v[66:67], off offset:2432
	global_load_dword v84, v[66:67], off offset:3200
	global_load_dword v85, v[66:67], off offset:3968
	global_load_dword v86, v[70:71], off offset:896
	global_load_dword v87, v[70:71], off offset:1664
	v_mov_b64_e32 v[50:51], v[144:145]

; template <int MODE>
; __device__ __forceinline__ void rwkv_scan_unit(int wid_s, const bf16* SIbh_, bf16* Yb_, int ystride, int quarter, float* ldsf) {
;     ...
;     if (wv == 4) SCAN_CONVERT(0);
;     ...
;         } else {
;             const int cn = ch + 1;
;             if (cn < 128 && (cn % 3) == hw) SCAN_CONVERT(cn);
;         }
.LBB0_1402:
	s_waitcnt lgkmcnt(0)
	s_barrier
	s_and_saveexec_b64 s[8:9], s[2:3]
	s_xor_b64 s[8:9], exec, s[8:9]
	s_cbranch_execz .LBB0_1412
	s_and_saveexec_b64 s[10:11], s[4:5]
	s_xor_b64 s[10:11], exec, s[10:11]
	s_cbranch_execz .LBB0_1408
	s_add_i32 s14, s0, 1
	v_readfirstlane_b32 s15, v56
	s_mul_i32 s17, s14, 0xab
	s_lshr_b32 s17, s17, 9
	s_mul_i32 s17, s17, 3
	s_sub_i32 s17, s14, s17
	s_cmp_lg_u32 s17, s15
	s_cbranch_scc1 .Lmy_cv_tryA
	s_cmp_gt_u32 s14, 0x7f
	s_cbranch_scc1 .Lmy_cv_done
	s_and_b32 s16, s14, 3
	s_mulk_i32 s16, 0x6000
	v_mov_b32_e32 v98, 1.0
	v_lshrrev_b32_e32 v63, 10, v57
	v_mul_u32_u24_e32 v63, 0x3000, v63
	v_bfe_u32 v99, v57, 5, 5
	v_lshl_add_u32 v63, v99, 3, v63
	v_add_u32_e32 v63, s16, v63
	s_cmp_lg_u32 s14, 1
	s_cbranch_scc1 .Lmy_cv_B
	s_waitcnt vmcnt(0)
	v_mov_b32_e32 v72, 1.0
	v_mov_b32_e32 v73, 1.0
	v_lshlrev_b32_e32 v78, 16, v80
	v_and_b32_e32 v79, 0xffff0000, v80
	v_sub_f32_e32 v78, 1.0, v78
	v_sub_f32_e32 v79, 1.0, v79
	v_mul_f32_e32 v72, v72, v78
	v_mul_f32_e32 v73, v73, v79
	v_lshlrev_b32_e32 v78, 16, v81
	v_and_b32_e32 v79, 0xffff0000, v81
	v_sub_f32_e32 v78, 1.0, v78
	v_sub_f32_e32 v79, 1.0, v79
	v_mul_f32_e32 v72, v72, v78
	v_mul_f32_e32 v73, v73, v79
	v_lshlrev_b32_e32 v78, 16, v82
	v_and_b32_e32 v79, 0xffff0000, v82
	v_sub_f32_e32 v78, 1.0, v78
	v_sub_f32_e32 v79, 1.0, v79
	v_mul_f32_e32 v72, v72, v78
	v_mul_f32_e32 v73, v73, v79
	v_lshlrev_b32_e32 v78, 16, v83
	v_and_b32_e32 v79, 0xffff0000, v83
	v_sub_f32_e32 v78, 1.0, v78
	v_sub_f32_e32 v79, 1.0, v79
	v_mul_f32_e32 v72, v72, v78
	v_mul_f32_e32 v73, v73, v79
	v_lshlrev_b32_e32 v78, 16, v84
	v_and_b32_e32 v79, 0xffff0000, v84
	v_sub_f32_e32 v78, 1.0, v78
	v_sub_f32_e32 v79, 1.0, v79
	v_mul_f32_e32 v72, v72, v78
	v_mul_f32_e32 v73, v73, v79
	v_lshlrev_b32_e32 v78, 16, v85
	v_and_b32_e32 v79, 0xffff0000, v85
	v_sub_f32_e32 v78, 1.0, v78
	v_sub_f32_e32 v79, 1.0, v79
	v_mul_f32_e32 v72, v72, v78
	v_mul_f32_e32 v73, v73, v79
	v_lshlrev_b32_e32 v78, 16, v86
	v_and_b32_e32 v79, 0xffff0000, v86
	v_sub_f32_e32 v78, 1.0, v78
	v_sub_f32_e32 v79, 1.0, v79
	v_mul_f32_e32 v72, v72, v78
	v_mul_f32_e32 v73, v73, v79
	v_lshlrev_b32_e32 v78, 16, v87
	v_and_b32_e32 v79, 0xffff0000, v87
	v_sub_f32_e32 v78, 1.0, v78
	v_sub_f32_e32 v79, 1.0, v79
	v_mul_f32_e32 v72, v72, v78
	v_mul_f32_e32 v73, v73, v79
	v_cmp_gt_u32_e32 vcc, 0x400, v57
	s_nop 1
	v_cndmask_b32_e32 v72, v72, v98, vcc
	v_cndmask_b32_e32 v73, v73, v98, vcc
	v_lshlrev_b32_e32 v78, 16, v1
	v_and_b32_e32 v79, 0xffff0000, v1
	v_sub_f32_e32 v78, 1.0, v78
	v_sub_f32_e32 v79, 1.0, v79
	v_mul_f32_e32 v74, v72, v78
	v_mul_f32_e32 v75, v73, v79
	v_lshlrev_b32_e32 v88, 16, v3
	v_and_b32_e32 v89, 0xffff0000, v3
	v_rcp_f32_e32 v76, v74
	v_rcp_f32_e32 v77, v75
	v_mul_f32_e32 v88, v88, v72
	v_mul_f32_e32 v89, v89, v73
	v_lshlrev_b32_e32 v90, 16, v0
	v_and_b32_e32 v91, 0xffff0000, v0
	v_mul_f32_e32 v90, v90, v74
	v_mul_f32_e32 v91, v91, v75
	v_lshlrev_b32_e32 v92, 16, v2
	v_and_b32_e32 v93, 0xffff0000, v2
	v_mul_f32_e32 v92, v92, v76
	v_mul_f32_e32 v93, v93, v77
	v_lshlrev_b32_e32 v94, 16, v4
	v_and_b32_e32 v95, 0xffff0000, v4
	v_mul_f32_e32 v94, v94, v76
	v_mul_f32_e32 v95, v95, v77
	v_lshlrev_b32_e32 v96, 16, v5
	v_and_b32_e32 v97, 0xffff0000, v5
	ds_write_b64 v63, v[90:91]
	ds_write_b64 v63, v[74:75] offset:256
	ds_write_b64 v63, v[92:93] offset:512
	ds_write_b64 v63, v[88:89] offset:768
	ds_write_b64 v63, v[94:95] offset:1024
	ds_write_b64 v63, v[96:97] offset:1280
	v_mov_b32_e32 v72, v74
	v_mov_b32_e32 v73, v75
	v_lshlrev_b32_e32 v78, 16, v7
	v_and_b32_e32 v79, 0xffff0000, v7
	v_sub_f32_e32 v78, 1.0, v78
	v_sub_f32_e32 v79, 1.0, v79
	v_mul_f32_e32 v74, v72, v78
	v_mul_f32_e32 v75, v73, v79
	v_lshlrev_b32_e32 v88, 16, v9
	v_and_b32_e32 v89, 0xffff0000, v9
	v_rcp_f32_e32 v76, v74
	v_rcp_f32_e32 v77, v75
	v_mul_f32_e32 v88, v88, v72
	v_mul_f32_e32 v89, v89, v73
	v_lshlrev_b32_e32 v90, 16, v6
	v_and_b32_e32 v91, 0xffff0000, v6
	v_mul_f32_e32 v90, v90, v74
	v_mul_f32_e32 v91, v91, v75
	v_lshlrev_b32_e32 v92, 16, v8
	v_and_b32_e32 v93, 0xffff0000, v8
	v_mul_f32_e32 v92, v92, v76
	v_mul_f32_e32 v93, v93, v77
	v_lshlrev_b32_e32 v94, 16, v10
	v_and_b32_e32 v95, 0xffff0000, v10
	v_mul_f32_e32 v94, v94, v76
	v_mul_f32_e32 v95, v95, v77
	v_lshlrev_b32_e32 v96, 16, v11
	v_and_b32_e32 v97, 0xffff0000, v11
	ds_write_b64 v63, v[90:91] offset:1536
	ds_write_b64 v63, v[74:75] offset:1792
	ds_write_b64 v63, v[92:93] offset:2048
	ds_write_b64 v63, v[88:89] offset:2304
	ds_write_b64 v63, v[94:95] offset:2560
	ds_write_b64 v63, v[96:97] offset:2816
	v_mov_b32_e32 v72, v74
	v_mov_b32_e32 v73, v75
	v_lshlrev_b32_e32 v78, 16, v13
	v_and_b32_e32 v79, 0xffff0000, v13
	v_sub_f32_e32 v78, 1.0, v78
	v_sub_f32_e32 v79, 1.0, v79
	v_mul_f32_e32 v74, v72, v78
	v_mul_f32_e32 v75, v73, v79
	v_lshlrev_b32_e32 v88, 16, v15
	v_and_b32_e32 v89, 0xffff0000, v15
	v_rcp_f32_e32 v76, v74
	v_rcp_f32_e32 v77, v75
	v_mul_f32_e32 v88, v88, v72
	v_mul_f32_e32 v89, v89, v73
	v_lshlrev_b32_e32 v90, 16, v12
	v_and_b32_e32 v91, 0xffff0000, v12
	v_mul_f32_e32 v90, v90, v74
	v_mul_f32_e32 v91, v91, v75
	v_lshlrev_b32_e32 v92, 16, v14
	v_and_b32_e32 v93, 0xffff0000, v14
	v_mul_f32_e32 v92, v92, v76
	v_mul_f32_e32 v93, v93, v77
	v_lshlrev_b32_e32 v94, 16, v16
	v_and_b32_e32 v95, 0xffff0000, v16
	v_mul_f32_e32 v94, v94, v76
	v_mul_f32_e32 v95, v95, v77
	v_lshlrev_b32_e32 v96, 16, v17
	v_and_b32_e32 v97, 0xffff0000, v17
	ds_write_b64 v63, v[90:91] offset:3072
	ds_write_b64 v63, v[74:75] offset:3328
	ds_write_b64 v63, v[92:93] offset:3584
	ds_write_b64 v63, v[88:89] offset:3840
	ds_write_b64 v63, v[94:95] offset:4096
	ds_write_b64 v63, v[96:97] offset:4352
	v_mov_b32_e32 v72, v74
	v_mov_b32_e32 v73, v75
	v_lshlrev_b32_e32 v78, 16, v19
	v_and_b32_e32 v79, 0xffff0000, v19
	v_sub_f32_e32 v78, 1.0, v78
	v_sub_f32_e32 v79, 1.0, v79
	v_mul_f32_e32 v74, v72, v78
	v_mul_f32_e32 v75, v73, v79
	v_lshlrev_b32_e32 v88, 16, v21
	v_and_b32_e32 v89, 0xffff0000, v21
	v_rcp_f32_e32 v76, v74
	v_rcp_f32_e32 v77, v75
	v_mul_f32_e32 v88, v88, v72
	v_mul_f32_e32 v89, v89, v73
	v_lshlrev_b32_e32 v90, 16, v18
	v_and_b32_e32 v91, 0xffff0000, v18
	v_mul_f32_e32 v90, v90, v74
	v_mul_f32_e32 v91, v91, v75
	v_lshlrev_b32_e32 v92, 16, v20
	v_and_b32_e32 v93, 0xffff0000, v20
	v_mul_f32_e32 v92, v92, v76
	v_mul_f32_e32 v93, v93, v77
	v_lshlrev_b32_e32 v94, 16, v22
	v_and_b32_e32 v95, 0xffff0000, v22
	v_mul_f32_e32 v94, v94, v76
	v_mul_f32_e32 v95, v95, v77
	v_lshlrev_b32_e32 v96, 16, v23
	v_and_b32_e32 v97, 0xffff0000, v23
	ds_write_b64 v63, v[90:91] offset:4608
	ds_write_b64 v63, v[74:75] offset:4864
	ds_write_b64 v63, v[92:93] offset:5120
	ds_write_b64 v63, v[88:89] offset:5376
	ds_write_b64 v63, v[94:95] offset:5632
	ds_write_b64 v63, v[96:97] offset:5888
	v_mov_b32_e32 v72, v74
	v_mov_b32_e32 v73, v75
.Lmy_cv_B:
	v_lshlrev_b32_e32 v78, 16, v25
	v_and_b32_e32 v79, 0xffff0000, v25
	v_sub_f32_e32 v78, 1.0, v78
	v_sub_f32_e32 v79, 1.0, v79
	v_mul_f32_e32 v74, v72, v78
	v_mul_f32_e32 v75, v73, v79
	v_lshlrev_b32_e32 v88, 16, v27
	v_and_b32_e32 v89, 0xffff0000, v27
	v_rcp_f32_e32 v76, v74
	v_rcp_f32_e32 v77, v75
	v_mul_f32_e32 v88, v88, v72
	v_mul_f32_e32 v89, v89, v73
	v_lshlrev_b32_e32 v90, 16, v24
	v_and_b32_e32 v91, 0xffff0000, v24
	v_mul_f32_e32 v90, v90, v74
	v_mul_f32_e32 v91, v91, v75
	v_lshlrev_b32_e32 v92, 16, v26
	v_and_b32_e32 v93, 0xffff0000, v26
	v_mul_f32_e32 v92, v92, v76
	v_mul_f32_e32 v93, v93, v77
	v_lshlrev_b32_e32 v94, 16, v28
	v_and_b32_e32 v95, 0xffff0000, v28
	v_mul_f32_e32 v94, v94, v76
	v_mul_f32_e32 v95, v95, v77
	v_lshlrev_b32_e32 v96, 16, v29
	v_and_b32_e32 v97, 0xffff0000, v29
	ds_write_b64 v63, v[90:91] offset:6144
	ds_write_b64 v63, v[74:75] offset:6400
	ds_write_b64 v63, v[92:93] offset:6656
	ds_write_b64 v63, v[88:89] offset:6912
	ds_write_b64 v63, v[94:95] offset:7168
	ds_write_b64 v63, v[96:97] offset:7424
	v_mov_b32_e32 v72, v74
	v_mov_b32_e32 v73, v75
	v_lshlrev_b32_e32 v78, 16, v31
	v_and_b32_e32 v79, 0xffff0000, v31
	v_sub_f32_e32 v78, 1.0, v78
	v_sub_f32_e32 v79, 1.0, v79
	v_mul_f32_e32 v74, v72, v78
	v_mul_f32_e32 v75, v73, v79
	v_lshlrev_b32_e32 v88, 16, v33
	v_and_b32_e32 v89, 0xffff0000, v33
	v_rcp_f32_e32 v76, v74
	v_rcp_f32_e32 v77, v75
	v_mul_f32_e32 v88, v88, v72
	v_mul_f32_e32 v89, v89, v73
	v_lshlrev_b32_e32 v90, 16, v30
	v_and_b32_e32 v91, 0xffff0000, v30
	v_mul_f32_e32 v90, v90, v74
	v_mul_f32_e32 v91, v91, v75
	v_lshlrev_b32_e32 v92, 16, v32
	v_and_b32_e32 v93, 0xffff0000, v32
	v_mul_f32_e32 v92, v92, v76
	v_mul_f32_e32 v93, v93, v77
	v_lshlrev_b32_e32 v94, 16, v34
	v_and_b32_e32 v95, 0xffff0000, v34
	v_mul_f32_e32 v94, v94, v76
	v_mul_f32_e32 v95, v95, v77
	v_lshlrev_b32_e32 v96, 16, v35
	v_and_b32_e32 v97, 0xffff0000, v35
	ds_write_b64 v63, v[90:91] offset:7680
	ds_write_b64 v63, v[74:75] offset:7936
	ds_write_b64 v63, v[92:93] offset:8192
	ds_write_b64 v63, v[88:89] offset:8448
	ds_write_b64 v63, v[94:95] offset:8704
	ds_write_b64 v63, v[96:97] offset:8960
	v_mov_b32_e32 v72, v74
	v_mov_b32_e32 v73, v75
	v_lshlrev_b32_e32 v78, 16, v37
	v_and_b32_e32 v79, 0xffff0000, v37
	v_sub_f32_e32 v78, 1.0, v78
	v_sub_f32_e32 v79, 1.0, v79
	v_mul_f32_e32 v74, v72, v78
	v_mul_f32_e32 v75, v73, v79
	v_lshlrev_b32_e32 v88, 16, v39
	v_and_b32_e32 v89, 0xffff0000, v39
	v_rcp_f32_e32 v76, v74
	v_rcp_f32_e32 v77, v75
	v_mul_f32_e32 v88, v88, v72
	v_mul_f32_e32 v89, v89, v73
	v_lshlrev_b32_e32 v90, 16, v36
	v_and_b32_e32 v91, 0xffff0000, v36
	v_mul_f32_e32 v90, v90, v74
	v_mul_f32_e32 v91, v91, v75
	v_lshlrev_b32_e32 v92, 16, v38
	v_and_b32_e32 v93, 0xffff0000, v38
	v_mul_f32_e32 v92, v92, v76
	v_mul_f32_e32 v93, v93, v77
	v_lshlrev_b32_e32 v94, 16, v40
	v_and_b32_e32 v95, 0xffff0000, v40
	v_mul_f32_e32 v94, v94, v76
	v_mul_f32_e32 v95, v95, v77
	v_lshlrev_b32_e32 v96, 16, v41
	v_and_b32_e32 v97, 0xffff0000, v41
	ds_write_b64 v63, v[90:91] offset:9216
	ds_write_b64 v63, v[74:75] offset:9472
	ds_write_b64 v63, v[92:93] offset:9728
	ds_write_b64 v63, v[88:89] offset:9984
	ds_write_b64 v63, v[94:95] offset:10240
	ds_write_b64 v63, v[96:97] offset:10496
	v_mov_b32_e32 v72, v74
	v_mov_b32_e32 v73, v75
	v_lshlrev_b32_e32 v78, 16, v43
	v_and_b32_e32 v79, 0xffff0000, v43
	v_sub_f32_e32 v78, 1.0, v78
	v_sub_f32_e32 v79, 1.0, v79
	v_mul_f32_e32 v74, v72, v78
	v_mul_f32_e32 v75, v73, v79
	v_lshlrev_b32_e32 v88, 16, v45
	v_and_b32_e32 v89, 0xffff0000, v45
	v_rcp_f32_e32 v76, v74
	v_rcp_f32_e32 v77, v75
	v_mul_f32_e32 v88, v88, v72
	v_mul_f32_e32 v89, v89, v73
	v_lshlrev_b32_e32 v90, 16, v42
	v_and_b32_e32 v91, 0xffff0000, v42
	v_mul_f32_e32 v90, v90, v74
	v_mul_f32_e32 v91, v91, v75
	v_lshlrev_b32_e32 v92, 16, v44
	v_and_b32_e32 v93, 0xffff0000, v44
	v_mul_f32_e32 v92, v92, v76
	v_mul_f32_e32 v93, v93, v77
	v_lshlrev_b32_e32 v94, 16, v46
	v_and_b32_e32 v95, 0xffff0000, v46
	v_mul_f32_e32 v94, v94, v76
	v_mul_f32_e32 v95, v95, v77
	v_lshlrev_b32_e32 v96, 16, v47
	v_and_b32_e32 v97, 0xffff0000, v47
	ds_write_b64 v63, v[90:91] offset:10752
	ds_write_b64 v63, v[74:75] offset:11008
	ds_write_b64 v63, v[92:93] offset:11264
	ds_write_b64 v63, v[88:89] offset:11520
	ds_write_b64 v63, v[94:95] offset:11776
	ds_write_b64 v63, v[96:97] offset:12032
	v_mov_b32_e32 v72, v74
	v_mov_b32_e32 v73, v75
	s_add_i32 s16, s14, 3
	s_cmp_gt_u32 s16, 0x7f
	s_cbranch_scc1 .Lmy_cv_done
; template <int MODE>
; __device__ __forceinline__ void rwkv_scan_unit(int wid_s, const bf16* SIbh_, bf16* Yb_, int ystride, int quarter, float* ldsf) {
;     ...
;         } else {
;             const int cn = ch + 1;
;             if (cn < 128 && (cn % 3) == hw) SCAN_CONVERT(cn);
;         }
	s_mul_i32 s12, s16, 0x3000
	s_mov_b32 s13, 0
	v_lshl_add_u64 v[64:65], v[50:51], 0, s[12:13]
	v_lshrrev_b32_e32 v66, 10, v57
	v_mul_u32_u24_e32 v66, 0x1800, v66
	v_mov_b32_e32 v67, 0
	v_sub_co_u32_e32 v66, vcc, v64, v66
	s_nop 1
	v_subb_co_u32_e32 v67, vcc, v65, v67, vcc
	s_movk_i32 s14, 0xf00
	s_mov_b32 s15, 0
	v_lshl_add_u64 v[68:69], v[64:65], 0, s[14:15]
	v_lshl_add_u64 v[70:71], v[66:67], 0, s[14:15]
	global_load_dword v0, v[64:65], off
	global_load_dword v1, v[64:65], off offset:128
	global_load_dword v2, v[64:65], off offset:256
	global_load_dword v3, v[64:65], off offset:384
	global_load_dword v4, v[64:65], off offset:512
	global_load_dword v5, v[64:65], off offset:640
	global_load_dword v6, v[64:65], off offset:768
	global_load_dword v7, v[64:65], off offset:896
	global_load_dword v8, v[64:65], off offset:1024
	global_load_dword v9, v[64:65], off offset:1152
	global_load_dword v10, v[64:65], off offset:1280
	global_load_dword v11, v[64:65], off offset:1408
	global_load_dword v12, v[64:65], off offset:1536
	global_load_dword v13, v[64:65], off offset:1664
	global_load_dword v14, v[64:65], off offset:1792
	global_load_dword v15, v[64:65], off offset:1920
	global_load_dword v16, v[64:65], off offset:2048
	global_load_dword v17, v[64:65], off offset:2176
	global_load_dword v18, v[64:65], off offset:2304
	global_load_dword v19, v[64:65], off offset:2432
	global_load_dword v20, v[64:65], off offset:2560
	global_load_dword v21, v[64:65], off offset:2688
	global_load_dword v22, v[64:65], off offset:2816
	global_load_dword v23, v[64:65], off offset:2944
	global_load_dword v24, v[64:65], off offset:3072
	global_load_dword v25, v[64:65], off offset:3200
	global_load_dword v26, v[64:65], off offset:3328
	global_load_dword v27, v[64:65], off offset:3456
	global_load_dword v28, v[64:65], off offset:3584
	global_load_dword v29, v[64:65], off offset:3712
	global_load_dword v30, v[64:65], off offset:3840
	global_load_dword v31, v[64:65], off offset:3968
	global_load_dword v32, v[68:69], off offset:256
	global_load_dword v33, v[68:69], off offset:384
	global_load_dword v34, v[68:69], off offset:512
	global_load_dword v35, v[68:69], off offset:640
	global_load_dword v36, v[68:69], off offset:768
	global_load_dword v37, v[68:69], off offset:896
	global_load_dword v38, v[68:69], off offset:1024
	global_load_dword v39, v[68:69], off offset:1152
	global_load_dword v40, v[68:69], off offset:1280
	global_load_dword v41, v[68:69], off offset:1408
	global_load_dword v42, v[68:69], off offset:1536
	global_load_dword v43, v[68:69], off offset:1664
	global_load_dword v44, v[68:69], off offset:1792
	global_load_dword v45, v[68:69], off offset:1920
	global_load_dword v46, v[68:69], off offset:2048
	global_load_dword v47, v[68:69], off offset:2176
	global_load_dword v80, v[66:67], off offset:128
	global_load_dword v81, v[66:67], off offset:896
	global_load_dword v82, v[66:67], off offset:1664
	global_load_dword v83, v[66:67], off offset:2432
	global_load_dword v84, v[66:67], off offset:3200
	global_load_dword v85, v[66:67], off offset:3968
	global_load_dword v86, v[70:71], off offset:896
	global_load_dword v87, v[70:71], off offset:1664
	s_branch .Lmy_cv_done
.Lmy_cv_tryA:
	s_add_i32 s17, s17, 1
	s_cmp_eq_u32 s17, 3
	s_cselect_b32 s17, 0, s17
	s_cmp_lg_u32 s17, s15
	s_cbranch_scc1 .Lmy_cv_done
	s_add_i32 s16, s14, 1
	s_cmp_gt_u32 s16, 0x7f
	s_cbranch_scc1 .Lmy_cv_done
	s_and_b32 s16, s16, 3
	s_mulk_i32 s16, 0x6000
	v_mov_b32_e32 v98, 1.0
	v_lshrrev_b32_e32 v63, 10, v57
	v_mul_u32_u24_e32 v63, 0x3000, v63
	v_bfe_u32 v99, v57, 5, 5
	v_lshl_add_u32 v63, v99, 3, v63
	v_add_u32_e32 v63, s16, v63
	s_waitcnt vmcnt(0)
	v_mov_b32_e32 v72, 1.0
	v_mov_b32_e32 v73, 1.0
	v_lshlrev_b32_e32 v78, 16, v80
	v_and_b32_e32 v79, 0xffff0000, v80
	v_sub_f32_e32 v78, 1.0, v78
	v_sub_f32_e32 v79, 1.0, v79
	v_mul_f32_e32 v72, v72, v78
	v_mul_f32_e32 v73, v73, v79
	v_lshlrev_b32_e32 v78, 16, v81
	v_and_b32_e32 v79, 0xffff0000, v81
	v_sub_f32_e32 v78, 1.0, v78
	v_sub_f32_e32 v79, 1.0, v79
	v_mul_f32_e32 v72, v72, v78
	v_mul_f32_e32 v73, v73, v79
	v_lshlrev_b32_e32 v78, 16, v82
	v_and_b32_e32 v79, 0xffff0000, v82
	v_sub_f32_e32 v78, 1.0, v78
	v_sub_f32_e32 v79, 1.0, v79
	v_mul_f32_e32 v72, v72, v78
	v_mul_f32_e32 v73, v73, v79
	v_lshlrev_b32_e32 v78, 16, v83
	v_and_b32_e32 v79, 0xffff0000, v83
	v_sub_f32_e32 v78, 1.0, v78
	v_sub_f32_e32 v79, 1.0, v79
	v_mul_f32_e32 v72, v72, v78
	v_mul_f32_e32 v73, v73, v79
	v_lshlrev_b32_e32 v78, 16, v84
	v_and_b32_e32 v79, 0xffff0000, v84
	v_sub_f32_e32 v78, 1.0, v78
	v_sub_f32_e32 v79, 1.0, v79
	v_mul_f32_e32 v72, v72, v78
	v_mul_f32_e32 v73, v73, v79
	v_lshlrev_b32_e32 v78, 16, v85
	v_and_b32_e32 v79, 0xffff0000, v85
	v_sub_f32_e32 v78, 1.0, v78
	v_sub_f32_e32 v79, 1.0, v79
	v_mul_f32_e32 v72, v72, v78
	v_mul_f32_e32 v73, v73, v79
	v_lshlrev_b32_e32 v78, 16, v86
	v_and_b32_e32 v79, 0xffff0000, v86
	v_sub_f32_e32 v78, 1.0, v78
	v_sub_f32_e32 v79, 1.0, v79
	v_mul_f32_e32 v72, v72, v78
	v_mul_f32_e32 v73, v73, v79
	v_lshlrev_b32_e32 v78, 16, v87
	v_and_b32_e32 v79, 0xffff0000, v87
	v_sub_f32_e32 v78, 1.0, v78
	v_sub_f32_e32 v79, 1.0, v79
	v_mul_f32_e32 v72, v72, v78
	v_mul_f32_e32 v73, v73, v79
	v_cmp_gt_u32_e32 vcc, 0x400, v57
	s_nop 1
	v_cndmask_b32_e32 v72, v72, v98, vcc
	v_cndmask_b32_e32 v73, v73, v98, vcc
	v_lshlrev_b32_e32 v78, 16, v1
	v_and_b32_e32 v79, 0xffff0000, v1
	v_sub_f32_e32 v78, 1.0, v78
	v_sub_f32_e32 v79, 1.0, v79
	v_mul_f32_e32 v74, v72, v78
	v_mul_f32_e32 v75, v73, v79
	v_lshlrev_b32_e32 v88, 16, v3
	v_and_b32_e32 v89, 0xffff0000, v3
	v_rcp_f32_e32 v76, v74
	v_rcp_f32_e32 v77, v75
	v_mul_f32_e32 v88, v88, v72
	v_mul_f32_e32 v89, v89, v73
	v_lshlrev_b32_e32 v90, 16, v0
	v_and_b32_e32 v91, 0xffff0000, v0
	v_mul_f32_e32 v90, v90, v74
	v_mul_f32_e32 v91, v91, v75
	v_lshlrev_b32_e32 v92, 16, v2
	v_and_b32_e32 v93, 0xffff0000, v2
	v_mul_f32_e32 v92, v92, v76
	v_mul_f32_e32 v93, v93, v77
	v_lshlrev_b32_e32 v94, 16, v4
	v_and_b32_e32 v95, 0xffff0000, v4
	v_mul_f32_e32 v94, v94, v76
	v_mul_f32_e32 v95, v95, v77
	v_lshlrev_b32_e32 v96, 16, v5
	v_and_b32_e32 v97, 0xffff0000, v5
	ds_write_b64 v63, v[90:91]
	ds_write_b64 v63, v[74:75] offset:256
	ds_write_b64 v63, v[92:93] offset:512
	ds_write_b64 v63, v[88:89] offset:768
	ds_write_b64 v63, v[94:95] offset:1024
	ds_write_b64 v63, v[96:97] offset:1280
	v_mov_b32_e32 v72, v74
	v_mov_b32_e32 v73, v75
	v_lshlrev_b32_e32 v78, 16, v7
	v_and_b32_e32 v79, 0xffff0000, v7
	v_sub_f32_e32 v78, 1.0, v78
	v_sub_f32_e32 v79, 1.0, v79
	v_mul_f32_e32 v74, v72, v78
	v_mul_f32_e32 v75, v73, v79
	v_lshlrev_b32_e32 v88, 16, v9
	v_and_b32_e32 v89, 0xffff0000, v9
	v_rcp_f32_e32 v76, v74
	v_rcp_f32_e32 v77, v75
	v_mul_f32_e32 v88, v88, v72
	v_mul_f32_e32 v89, v89, v73
	v_lshlrev_b32_e32 v90, 16, v6
	v_and_b32_e32 v91, 0xffff0000, v6
	v_mul_f32_e32 v90, v90, v74
	v_mul_f32_e32 v91, v91, v75
	v_lshlrev_b32_e32 v92, 16, v8
	v_and_b32_e32 v93, 0xffff0000, v8
	v_mul_f32_e32 v92, v92, v76
	v_mul_f32_e32 v93, v93, v77
	v_lshlrev_b32_e32 v94, 16, v10
	v_and_b32_e32 v95, 0xffff0000, v10
	v_mul_f32_e32 v94, v94, v76
	v_mul_f32_e32 v95, v95, v77
	v_lshlrev_b32_e32 v96, 16, v11
	v_and_b32_e32 v97, 0xffff0000, v11
	ds_write_b64 v63, v[90:91] offset:1536
	ds_write_b64 v63, v[74:75] offset:1792
	ds_write_b64 v63, v[92:93] offset:2048
	ds_write_b64 v63, v[88:89] offset:2304
	ds_write_b64 v63, v[94:95] offset:2560
	ds_write_b64 v63, v[96:97] offset:2816
	v_mov_b32_e32 v72, v74
	v_mov_b32_e32 v73, v75
	v_lshlrev_b32_e32 v78, 16, v13
	v_and_b32_e32 v79, 0xffff0000, v13
	v_sub_f32_e32 v78, 1.0, v78
	v_sub_f32_e32 v79, 1.0, v79
	v_mul_f32_e32 v74, v72, v78
	v_mul_f32_e32 v75, v73, v79
	v_lshlrev_b32_e32 v88, 16, v15
	v_and_b32_e32 v89, 0xffff0000, v15
	v_rcp_f32_e32 v76, v74
	v_rcp_f32_e32 v77, v75
	v_mul_f32_e32 v88, v88, v72
	v_mul_f32_e32 v89, v89, v73
	v_lshlrev_b32_e32 v90, 16, v12
	v_and_b32_e32 v91, 0xffff0000, v12
	v_mul_f32_e32 v90, v90, v74
	v_mul_f32_e32 v91, v91, v75
	v_lshlrev_b32_e32 v92, 16, v14
	v_and_b32_e32 v93, 0xffff0000, v14
	v_mul_f32_e32 v92, v92, v76
	v_mul_f32_e32 v93, v93, v77
	v_lshlrev_b32_e32 v94, 16, v16
	v_and_b32_e32 v95, 0xffff0000, v16
	v_mul_f32_e32 v94, v94, v76
	v_mul_f32_e32 v95, v95, v77
	v_lshlrev_b32_e32 v96, 16, v17
	v_and_b32_e32 v97, 0xffff0000, v17
	ds_write_b64 v63, v[90:91] offset:3072
	ds_write_b64 v63, v[74:75] offset:3328
	ds_write_b64 v63, v[92:93] offset:3584
	ds_write_b64 v63, v[88:89] offset:3840
	ds_write_b64 v63, v[94:95] offset:4096
	ds_write_b64 v63, v[96:97] offset:4352
	v_mov_b32_e32 v72, v74
	v_mov_b32_e32 v73, v75
	v_lshlrev_b32_e32 v78, 16, v19
	v_and_b32_e32 v79, 0xffff0000, v19
	v_sub_f32_e32 v78, 1.0, v78
	v_sub_f32_e32 v79, 1.0, v79
	v_mul_f32_e32 v74, v72, v78
	v_mul_f32_e32 v75, v73, v79
	v_lshlrev_b32_e32 v88, 16, v21
	v_and_b32_e32 v89, 0xffff0000, v21
	v_rcp_f32_e32 v76, v74
	v_rcp_f32_e32 v77, v75
	v_mul_f32_e32 v88, v88, v72
	v_mul_f32_e32 v89, v89, v73
	v_lshlrev_b32_e32 v90, 16, v18
	v_and_b32_e32 v91, 0xffff0000, v18
	v_mul_f32_e32 v90, v90, v74
	v_mul_f32_e32 v91, v91, v75
	v_lshlrev_b32_e32 v92, 16, v20
	v_and_b32_e32 v93, 0xffff0000, v20
	v_mul_f32_e32 v92, v92, v76
	v_mul_f32_e32 v93, v93, v77
	v_lshlrev_b32_e32 v94, 16, v22
	v_and_b32_e32 v95, 0xffff0000, v22
	v_mul_f32_e32 v94, v94, v76
	v_mul_f32_e32 v95, v95, v77
	v_lshlrev_b32_e32 v96, 16, v23
	v_and_b32_e32 v97, 0xffff0000, v23
	ds_write_b64 v63, v[90:91] offset:4608
	ds_write_b64 v63, v[74:75] offset:4864
	ds_write_b64 v63, v[92:93] offset:5120
	ds_write_b64 v63, v[88:89] offset:5376
	ds_write_b64 v63, v[94:95] offset:5632
	ds_write_b64 v63, v[96:97] offset:5888
	v_mov_b32_e32 v72, v74
	v_mov_b32_e32 v73, v75
; __device__ __forceinline__ unsigned f2bf(float f) { unsigned u = __builtin_bit_cast(unsigned, f); return (u + 0x7fffu + ((u >> 16) & 1u)) >> 16; }
; template <int MODE>
; __device__ __forceinline__ void rwkv_scan_unit(int wid_s, const bf16* SIbh_, bf16* Yb_, int ystride, int quarter, float* ldsf) {
;     ...
;         } else if (wv == 7) {
;             if (ch > 0) {
;                 const int s = lane >> 2, rr = lane & 3;
; #pragma unroll
;                 for (int mw = 0; mw < 4; ++mw) {
;                     const float* src = PYb + ((ch - 1) & 1) * (16 * 260) + s * 260 + mw * 64 + rr * 16;
;                     const f32x4 a = *(const f32x4*)src, b = *(const f32x4*)(src + 4), c = *(const f32x4*)(src + 8), d = *(const f32x4*)(src + 12);
;                     const float y = ((a.x + a.y) + (a.z + a.w)) + ((b.x + b.y) + (b.z + b.w)) + ((c.x + c.y) + (c.z + c.w)) + ((d.x + d.y) + (d.z + d.w));
;                     Yb[(size_t)((ch - 1) * 16 + s) * ystride + quarter * 16 + mw * 4 + rr] = (bf16)f2bf(y);
;                 }
;             }
.Lmy_cv_done:
.LBB0_1408:
	s_andn2_saveexec_b64 s[10:11], s[10:11]
	s_cbranch_execz .LBB0_1411
	s_cmp_eq_u32 s6, 0
	s_cbranch_scc1 .LBB0_1411
	s_bitcmp1_b32 s0, 0
	s_cselect_b32 s12, 0, 0x4100
	v_add_u32_e32 v63, s12, v59
	ds_read_b128 v[64:67], v63
	ds_read_b128 v[68:71], v63 offset:16
	ds_read_b128 v[72:75], v63 offset:32
	ds_read_b128 v[76:79], v63 offset:48
	s_movk_i32 s12, 0xc00
	v_mad_u64_u32 v[80:81], s[12:13], v62, s12, v[48:49]
	s_waitcnt lgkmcnt(3)
	v_add_f32_e32 v64, v64, v65
	v_add_f32_e32 v65, v66, v67
	v_add_f32_e32 v64, v64, v65
	s_waitcnt lgkmcnt(2)
	v_add_f32_e32 v65, v68, v69
	v_add_f32_e32 v66, v70, v71
	v_add_f32_e32 v65, v65, v66
	v_add_f32_e32 v64, v64, v65
	s_waitcnt lgkmcnt(1)
	v_add_f32_e32 v65, v72, v73
	v_add_f32_e32 v66, v74, v75
	v_add_f32_e32 v65, v65, v66
	v_add_f32_e32 v64, v64, v65
	s_waitcnt lgkmcnt(0)
	v_add_f32_e32 v65, v76, v77
	v_add_f32_e32 v66, v78, v79
	v_add_f32_e32 v65, v65, v66
	v_add_f32_e32 v64, v64, v65
	v_bfe_u32 v65, v64, 16, 1
	v_add3_u32 v68, v64, v65, s1
	ds_read_b128 v[64:67], v63 offset:256
	global_store_short_d16_hi v[80:81], v68, off
	ds_read_b128 v[68:71], v63 offset:272
	ds_read_b128 v[72:75], v63 offset:288
	ds_read_b128 v[76:79], v63 offset:304
	s_waitcnt lgkmcnt(3)
	v_add_f32_e32 v64, v64, v65
	v_add_f32_e32 v65, v66, v67
	v_add_f32_e32 v64, v64, v65
	s_waitcnt lgkmcnt(2)
	v_add_f32_e32 v65, v68, v69
	v_add_f32_e32 v66, v70, v71
	v_add_f32_e32 v65, v65, v66
	v_add_f32_e32 v64, v64, v65
	s_waitcnt lgkmcnt(1)
	v_add_f32_e32 v65, v72, v73
	v_add_f32_e32 v66, v74, v75
	v_add_f32_e32 v65, v65, v66
	v_add_f32_e32 v64, v64, v65
	s_waitcnt lgkmcnt(0)
	v_add_f32_e32 v65, v76, v77
	v_add_f32_e32 v66, v78, v79
	v_add_f32_e32 v65, v65, v66
	v_add_f32_e32 v64, v64, v65
	v_bfe_u32 v65, v64, 16, 1
	v_add3_u32 v68, v64, v65, s1
	ds_read_b128 v[64:67], v63 offset:512
	global_store_short_d16_hi v[80:81], v68, off offset:8
	ds_read_b128 v[68:71], v63 offset:528
	ds_read_b128 v[72:75], v63 offset:544
	ds_read_b128 v[76:79], v63 offset:560
	s_waitcnt lgkmcnt(3)
	v_add_f32_e32 v64, v64, v65
	v_add_f32_e32 v65, v66, v67
	v_add_f32_e32 v64, v64, v65
	s_waitcnt lgkmcnt(2)
	v_add_f32_e32 v65, v68, v69
	v_add_f32_e32 v66, v70, v71
	v_add_f32_e32 v65, v65, v66
	v_add_f32_e32 v64, v64, v65
	s_waitcnt lgkmcnt(1)
	v_add_f32_e32 v65, v72, v73
	v_add_f32_e32 v66, v74, v75
	v_add_f32_e32 v65, v65, v66
	v_add_f32_e32 v64, v64, v65
	s_waitcnt lgkmcnt(0)
	v_add_f32_e32 v65, v76, v77
	v_add_f32_e32 v66, v78, v79
	v_add_f32_e32 v65, v65, v66
	v_add_f32_e32 v64, v64, v65
	v_bfe_u32 v65, v64, 16, 1
	v_add3_u32 v68, v64, v65, s1
	ds_read_b128 v[64:67], v63 offset:768
	global_store_short_d16_hi v[80:81], v68, off offset:16
	ds_read_b128 v[68:71], v63 offset:784
	ds_read_b128 v[72:75], v63 offset:800
	ds_read_b128 v[76:79], v63 offset:816
	s_waitcnt lgkmcnt(3)
	v_add_f32_e32 v63, v64, v65
	v_add_f32_e32 v64, v66, v67
	v_add_f32_e32 v63, v63, v64
	s_waitcnt lgkmcnt(2)
	v_add_f32_e32 v64, v68, v69
	v_add_f32_e32 v65, v70, v71
	v_add_f32_e32 v64, v64, v65
	v_add_f32_e32 v63, v63, v64
	s_waitcnt lgkmcnt(1)
	v_add_f32_e32 v64, v72, v73
	v_add_f32_e32 v65, v74, v75
	v_add_f32_e32 v64, v64, v65
	v_add_f32_e32 v63, v63, v64
	s_waitcnt lgkmcnt(0)
	v_add_f32_e32 v64, v76, v77
	v_add_f32_e32 v65, v78, v79
	v_add_f32_e32 v64, v64, v65
	v_add_f32_e32 v63, v63, v64
	v_bfe_u32 v64, v63, 16, 1
	v_add3_u32 v63, v63, v64, s1
	global_store_short_d16_hi v[80:81], v63, off offset:24

; __device__ __forceinline__ float allreduce16(float x) { x += dppf<0xB1>(x); x += dppf<0x4E>(x); x += dppf<0x141>(x); x += dppf<0x140>(x); return x; }
; template <int MODE>
; __device__ __forceinline__ void rwkv_scan_unit(int wid_s, const bf16* SIbh_, bf16* Yb_, int ystride, int quarter, float* ldsf) {
;     ...
;         if (wv < 4) {
;             if (ch < 128) {
;                 const float* B = ldsf + (ch & 3) * (16 * 384);
;                 float* PY = PYb + (ch & 1) * (16 * 260) + wv * 64 + lane;
;                 const float* q = B;
;                 f32x4 r4 = *(const f32x4*)(q + c4), om4 = *(const f32x4*)(q + 64 + c4), k4 = *(const f32x4*)(q + 128 + c4), kk4 = *(const f32x4*)(q + 192 + c4), ka4 = *(const f32x4*)(q + 256 + c4);
;                 float v = q[320 + rowl];
;                 __builtin_amdgcn_s_setprio(3);
; #pragma unroll
;                 for (int s = 0; s < 16; ++s) {
;                     const float* qn = B + ((MODE & 2) ? 0 : ((s + 1) & 15)) * 384;
;                     const f32x4 nr4 = *(const f32x4*)(qn + c4), nom4 = *(const f32x4*)(qn + 64 + c4), nk4 = *(const f32x4*)(qn + 128 + c4), nkk4 = *(const f32x4*)(qn + 192 + c4), nka4 = *(const f32x4*)(qn + 256 + c4);
;                     const float nv = qn[320 + rowl];
;                     const f32x2 pa = Sa * (f32x2){kk4.x, kk4.y} + Sb * (f32x2){kk4.z, kk4.w};
;                     const float sa = (MODE & 1) ? (pa.x + pa.y) : allreduce16(pa.x + pa.y);
;                     Sa = Sa - Sa * (f32x2){om4.x, om4.y} + (f32x2){k4.x, k4.y} * v; Sb = Sb - Sb * (f32x2){om4.z, om4.w} + (f32x2){k4.z, k4.w} * v;
;                     Sa = Sa - (f32x2){ka4.x, ka4.y} * sa; Sb = Sb - (f32x2){ka4.z, ka4.w} * sa;
;                     const f32x2 py = Sa * (f32x2){r4.x, r4.y} + Sb * (f32x2){r4.z, r4.w};
;                     PY[s * 260] = py.x + py.y;
;                     r4 = nr4; om4 = nom4; k4 = nk4; kk4 = nkk4; ka4 = nka4; v = nv;
;                 }
.LBB0_1412:
	s_andn2_saveexec_b64 s[8:9], s[8:9]
	s_cbranch_execz .LBB0_1401
	s_cmp_eq_u32 s6, 0x180000
	s_cbranch_scc1 .LBB0_1401
	s_and_b32 s10, s0, 3
	s_mulk_i32 s10, 0x6000
	s_add_i32 s10, s10, 0
	v_lshl_add_u32 v105, v58, 2, s10
	v_lshl_add_u32 v107, v61, 2, s10
	s_bitcmp1_b32 s0, 0
	s_cselect_b32 s10, 0x4100, 0
	v_add_u32_e32 v63, s10, v60
	s_setprio 3
	ds_read_b128 v[72:75], v105 offset:768
	ds_read_b128 v[68:71], v105 offset:512
	ds_read_b128 v[76:79], v105 offset:1024
	ds_read_b128 v[64:67], v105
	ds_read2st64_b32 v[32:33], v107 offset0:5 offset1:11
	ds_read_b128 v[92:95], v105 offset:2304
	ds_read_b128 v[88:91], v105 offset:2048
	ds_read_b128 v[96:99], v105 offset:2560
	ds_read_b128 v[84:87], v105 offset:1536
	s_waitcnt lgkmcnt(0)
	v_pk_mul_f32 v[28:29], v[54:55], v[72:73]
	v_pk_fma_f32 v[28:29], v[52:53], v[74:75], v[28:29]
	v_add_f32_e32 v28, v28, v29
	s_nop 1
	v_add_f32_dpp v28, v28, v28 quad_perm:[1,0,3,2] row_mask:0xf bank_mask:0xf bound_ctrl:1
	s_nop 1
	v_add_f32_dpp v28, v28, v28 quad_perm:[2,3,0,1] row_mask:0xf bank_mask:0xf bound_ctrl:1
	v_pk_fma_f32 v[24:25], v[68:69], v[32:33], v[54:55] op_sel_hi:[1,0,1]
	v_pk_fma_f32 v[26:27], v[70:71], v[32:33], v[52:53] op_sel_hi:[1,0,1]
	v_add_f32_dpp v28, v28, v28 row_half_mirror row_mask:0xf bank_mask:0xf bound_ctrl:1
	ds_read_b128 v[8:11], v105 offset:3840
	ds_read_b128 v[4:7], v105 offset:3584
	ds_read_b128 v[12:15], v105 offset:4096
	ds_read_b128 v[0:3], v105 offset:3072
	ds_read2st64_b32 v[34:35], v107 offset0:17 offset1:23
	s_waitcnt lgkmcnt(5)
	v_add_f32_dpp v28, v28, v28 row_mirror row_mask:0xf bank_mask:0xf bound_ctrl:1
	v_pk_fma_f32 v[24:25], v[76:77], v[28:29], v[24:25] op_sel_hi:[1,0,1] neg_lo:[1,0,0] neg_hi:[1,0,0]
	v_pk_fma_f32 v[26:27], v[78:79], v[28:29], v[26:27] op_sel_hi:[1,0,1] neg_lo:[1,0,0] neg_hi:[1,0,0]
	v_pk_mul_f32 v[28:29], v[24:25], v[92:93]
	v_pk_fma_f32 v[28:29], v[26:27], v[94:95], v[28:29]
	v_add_f32_e32 v28, v28, v29
	v_pk_mul_f32 v[30:31], v[66:67], v[26:27]
	v_pk_fma_f32 v[30:31], v[64:65], v[24:25], v[30:31]
	v_add_f32_dpp v28, v28, v28 quad_perm:[1,0,3,2] row_mask:0xf bank_mask:0xf bound_ctrl:1
	v_add_f32_e32 v30, v30, v31
	ds_write_b32 v63, v30
	v_add_f32_dpp v28, v28, v28 quad_perm:[2,3,0,1] row_mask:0xf bank_mask:0xf bound_ctrl:1
	v_pk_fma_f32 v[54:55], v[88:89], v[32:33], v[24:25] op_sel:[0,1,0] op_sel_hi:[1,1,1]
	v_pk_fma_f32 v[52:53], v[90:91], v[32:33], v[26:27] op_sel:[0,1,0] op_sel_hi:[1,1,1]
	v_add_f32_dpp v28, v28, v28 row_half_mirror row_mask:0xf bank_mask:0xf bound_ctrl:1
	ds_read_b128 v[72:75], v105 offset:5376
	ds_read_b128 v[68:71], v105 offset:5120
	ds_read_b128 v[76:79], v105 offset:5632
	ds_read_b128 v[64:67], v105 offset:4608
	s_waitcnt lgkmcnt(4)
	v_add_f32_dpp v28, v28, v28 row_mirror row_mask:0xf bank_mask:0xf bound_ctrl:1
	v_pk_fma_f32 v[54:55], v[96:97], v[28:29], v[54:55] op_sel_hi:[1,0,1] neg_lo:[1,0,0] neg_hi:[1,0,0]
	v_pk_fma_f32 v[52:53], v[98:99], v[28:29], v[52:53] op_sel_hi:[1,0,1] neg_lo:[1,0,0] neg_hi:[1,0,0]
	v_pk_mul_f32 v[28:29], v[54:55], v[8:9]
	v_pk_fma_f32 v[28:29], v[52:53], v[10:11], v[28:29]
	v_add_f32_e32 v28, v28, v29
	v_pk_mul_f32 v[30:31], v[86:87], v[52:53]
	v_pk_fma_f32 v[30:31], v[84:85], v[54:55], v[30:31]
	v_add_f32_dpp v28, v28, v28 quad_perm:[1,0,3,2] row_mask:0xf bank_mask:0xf bound_ctrl:1
	v_add_f32_e32 v30, v30, v31
	ds_write_b32 v63, v30 offset:1040
	v_add_f32_dpp v28, v28, v28 quad_perm:[2,3,0,1] row_mask:0xf bank_mask:0xf bound_ctrl:1
	v_pk_fma_f32 v[24:25], v[4:5], v[34:35], v[54:55] op_sel_hi:[1,0,1]
	v_pk_fma_f32 v[26:27], v[6:7], v[34:35], v[52:53] op_sel_hi:[1,0,1]
	v_add_f32_dpp v28, v28, v28 row_half_mirror row_mask:0xf bank_mask:0xf bound_ctrl:1
	ds_read_b128 v[92:95], v105 offset:6912
	ds_read_b128 v[88:91], v105 offset:6656
	ds_read_b128 v[96:99], v105 offset:7168
	ds_read_b128 v[84:87], v105 offset:6144
	ds_read2st64_b32 v[32:33], v107 offset0:29 offset1:35
	s_waitcnt lgkmcnt(5)
	v_add_f32_dpp v28, v28, v28 row_mirror row_mask:0xf bank_mask:0xf bound_ctrl:1
	v_pk_fma_f32 v[24:25], v[12:13], v[28:29], v[24:25] op_sel_hi:[1,0,1] neg_lo:[1,0,0] neg_hi:[1,0,0]
	v_pk_fma_f32 v[26:27], v[14:15], v[28:29], v[26:27] op_sel_hi:[1,0,1] neg_lo:[1,0,0] neg_hi:[1,0,0]
	v_pk_mul_f32 v[28:29], v[24:25], v[72:73]
	v_pk_fma_f32 v[28:29], v[26:27], v[74:75], v[28:29]
	v_add_f32_e32 v28, v28, v29
	v_pk_mul_f32 v[30:31], v[2:3], v[26:27]
	v_pk_fma_f32 v[30:31], v[0:1], v[24:25], v[30:31]
	v_add_f32_dpp v28, v28, v28 quad_perm:[1,0,3,2] row_mask:0xf bank_mask:0xf bound_ctrl:1
	v_add_f32_e32 v30, v30, v31
	ds_write_b32 v63, v30 offset:2080
	v_add_f32_dpp v28, v28, v28 quad_perm:[2,3,0,1] row_mask:0xf bank_mask:0xf bound_ctrl:1
	v_pk_fma_f32 v[54:55], v[68:69], v[34:35], v[24:25] op_sel:[0,1,0] op_sel_hi:[1,1,1]
	v_pk_fma_f32 v[52:53], v[70:71], v[34:35], v[26:27] op_sel:[0,1,0] op_sel_hi:[1,1,1]
	v_add_f32_dpp v28, v28, v28 row_half_mirror row_mask:0xf bank_mask:0xf bound_ctrl:1
	ds_read_b128 v[8:11], v105 offset:8448
	ds_read_b128 v[4:7], v105 offset:8192
	ds_read_b128 v[12:15], v105 offset:8704
	ds_read_b128 v[0:3], v105 offset:7680
	s_waitcnt lgkmcnt(4)
; __device__ __forceinline__ float allreduce16(float x) { x += dppf<0xB1>(x); x += dppf<0x4E>(x); x += dppf<0x141>(x); x += dppf<0x140>(x); return x; }
; template <int MODE>
; __device__ __forceinline__ void rwkv_scan_unit(int wid_s, const bf16* SIbh_, bf16* Yb_, int ystride, int quarter, float* ldsf) {
;     ...
;                 for (int s = 0; s < 16; ++s) {
;                     const float* qn = B + ((MODE & 2) ? 0 : ((s + 1) & 15)) * 384;
;                     const f32x4 nr4 = *(const f32x4*)(qn + c4), nom4 = *(const f32x4*)(qn + 64 + c4), nk4 = *(const f32x4*)(qn + 128 + c4), nkk4 = *(const f32x4*)(qn + 192 + c4), nka4 = *(const f32x4*)(qn + 256 + c4);
;                     const float nv = qn[320 + rowl];
;                     const f32x2 pa = Sa * (f32x2){kk4.x, kk4.y} + Sb * (f32x2){kk4.z, kk4.w};
;                     const float sa = (MODE & 1) ? (pa.x + pa.y) : allreduce16(pa.x + pa.y);
;                     Sa = Sa - Sa * (f32x2){om4.x, om4.y} + (f32x2){k4.x, k4.y} * v; Sb = Sb - Sb * (f32x2){om4.z, om4.w} + (f32x2){k4.z, k4.w} * v;
;                     Sa = Sa - (f32x2){ka4.x, ka4.y} * sa; Sb = Sb - (f32x2){ka4.z, ka4.w} * sa;
;                     const f32x2 py = Sa * (f32x2){r4.x, r4.y} + Sb * (f32x2){r4.z, r4.w};
;                     PY[s * 260] = py.x + py.y;
;                     r4 = nr4; om4 = nom4; k4 = nk4; kk4 = nkk4; ka4 = nka4; v = nv;
;                 }
	v_add_f32_dpp v28, v28, v28 row_mirror row_mask:0xf bank_mask:0xf bound_ctrl:1
	v_pk_fma_f32 v[54:55], v[76:77], v[28:29], v[54:55] op_sel_hi:[1,0,1] neg_lo:[1,0,0] neg_hi:[1,0,0]
	v_pk_fma_f32 v[52:53], v[78:79], v[28:29], v[52:53] op_sel_hi:[1,0,1] neg_lo:[1,0,0] neg_hi:[1,0,0]
	v_pk_mul_f32 v[28:29], v[54:55], v[92:93]
	v_pk_fma_f32 v[28:29], v[52:53], v[94:95], v[28:29]
	v_add_f32_e32 v28, v28, v29
	v_pk_mul_f32 v[30:31], v[66:67], v[52:53]
	v_pk_fma_f32 v[30:31], v[64:65], v[54:55], v[30:31]
	v_add_f32_dpp v28, v28, v28 quad_perm:[1,0,3,2] row_mask:0xf bank_mask:0xf bound_ctrl:1
	v_add_f32_e32 v30, v30, v31
	ds_write_b32 v63, v30 offset:3120
	v_add_f32_dpp v28, v28, v28 quad_perm:[2,3,0,1] row_mask:0xf bank_mask:0xf bound_ctrl:1
	v_pk_fma_f32 v[24:25], v[88:89], v[32:33], v[54:55] op_sel_hi:[1,0,1]
	v_pk_fma_f32 v[26:27], v[90:91], v[32:33], v[52:53] op_sel_hi:[1,0,1]
	v_add_f32_dpp v28, v28, v28 row_half_mirror row_mask:0xf bank_mask:0xf bound_ctrl:1
	ds_read_b128 v[72:75], v105 offset:9984
	ds_read_b128 v[68:71], v105 offset:9728
	ds_read_b128 v[76:79], v105 offset:10240
	ds_read_b128 v[64:67], v105 offset:9216
	ds_read2st64_b32 v[34:35], v107 offset0:41 offset1:47
	s_waitcnt lgkmcnt(5)
	v_add_f32_dpp v28, v28, v28 row_mirror row_mask:0xf bank_mask:0xf bound_ctrl:1
	v_pk_fma_f32 v[24:25], v[96:97], v[28:29], v[24:25] op_sel_hi:[1,0,1] neg_lo:[1,0,0] neg_hi:[1,0,0]
	v_pk_fma_f32 v[26:27], v[98:99], v[28:29], v[26:27] op_sel_hi:[1,0,1] neg_lo:[1,0,0] neg_hi:[1,0,0]
	v_pk_mul_f32 v[28:29], v[24:25], v[8:9]
	v_pk_fma_f32 v[28:29], v[26:27], v[10:11], v[28:29]
	v_add_f32_e32 v28, v28, v29
	v_pk_mul_f32 v[30:31], v[86:87], v[26:27]
	v_pk_fma_f32 v[30:31], v[84:85], v[24:25], v[30:31]
	v_add_f32_dpp v28, v28, v28 quad_perm:[1,0,3,2] row_mask:0xf bank_mask:0xf bound_ctrl:1
	v_add_f32_e32 v30, v30, v31
	ds_write_b32 v63, v30 offset:4160
	v_add_f32_dpp v28, v28, v28 quad_perm:[2,3,0,1] row_mask:0xf bank_mask:0xf bound_ctrl:1
	v_pk_fma_f32 v[54:55], v[4:5], v[32:33], v[24:25] op_sel:[0,1,0] op_sel_hi:[1,1,1]
	v_pk_fma_f32 v[52:53], v[6:7], v[32:33], v[26:27] op_sel:[0,1,0] op_sel_hi:[1,1,1]
	v_add_f32_dpp v28, v28, v28 row_half_mirror row_mask:0xf bank_mask:0xf bound_ctrl:1
	ds_read_b128 v[92:95], v105 offset:11520
	ds_read_b128 v[88:91], v105 offset:11264
	ds_read_b128 v[96:99], v105 offset:11776
	ds_read_b128 v[84:87], v105 offset:10752
	s_waitcnt lgkmcnt(4)
	v_add_f32_dpp v28, v28, v28 row_mirror row_mask:0xf bank_mask:0xf bound_ctrl:1
	v_pk_fma_f32 v[54:55], v[12:13], v[28:29], v[54:55] op_sel_hi:[1,0,1] neg_lo:[1,0,0] neg_hi:[1,0,0]
	v_pk_fma_f32 v[52:53], v[14:15], v[28:29], v[52:53] op_sel_hi:[1,0,1] neg_lo:[1,0,0] neg_hi:[1,0,0]
	v_pk_mul_f32 v[28:29], v[54:55], v[72:73]
	v_pk_fma_f32 v[28:29], v[52:53], v[74:75], v[28:29]
	v_add_f32_e32 v28, v28, v29
	v_pk_mul_f32 v[30:31], v[2:3], v[52:53]
	v_pk_fma_f32 v[30:31], v[0:1], v[54:55], v[30:31]
	v_add_f32_dpp v28, v28, v28 quad_perm:[1,0,3,2] row_mask:0xf bank_mask:0xf bound_ctrl:1
	v_add_f32_e32 v30, v30, v31
	ds_write_b32 v63, v30 offset:5200
	v_add_f32_dpp v28, v28, v28 quad_perm:[2,3,0,1] row_mask:0xf bank_mask:0xf bound_ctrl:1
	v_pk_fma_f32 v[24:25], v[68:69], v[34:35], v[54:55] op_sel_hi:[1,0,1]
	v_pk_fma_f32 v[26:27], v[70:71], v[34:35], v[52:53] op_sel_hi:[1,0,1]
	v_add_f32_dpp v28, v28, v28 row_half_mirror row_mask:0xf bank_mask:0xf bound_ctrl:1
	ds_read_b128 v[8:11], v105 offset:13056
	ds_read_b128 v[4:7], v105 offset:12800
	ds_read_b128 v[12:15], v105 offset:13312
	ds_read_b128 v[0:3], v105 offset:12288
	ds_read2st64_b32 v[32:33], v107 offset0:53 offset1:59
	s_waitcnt lgkmcnt(5)
	v_add_f32_dpp v28, v28, v28 row_mirror row_mask:0xf bank_mask:0xf bound_ctrl:1
	v_pk_fma_f32 v[24:25], v[76:77], v[28:29], v[24:25] op_sel_hi:[1,0,1] neg_lo:[1,0,0] neg_hi:[1,0,0]
	v_pk_fma_f32 v[26:27], v[78:79], v[28:29], v[26:27] op_sel_hi:[1,0,1] neg_lo:[1,0,0] neg_hi:[1,0,0]
	v_pk_mul_f32 v[28:29], v[24:25], v[92:93]
	v_pk_fma_f32 v[28:29], v[26:27], v[94:95], v[28:29]
	v_add_f32_e32 v28, v28, v29
	v_pk_mul_f32 v[30:31], v[66:67], v[26:27]
	v_pk_fma_f32 v[30:31], v[64:65], v[24:25], v[30:31]
	v_add_f32_dpp v28, v28, v28 quad_perm:[1,0,3,2] row_mask:0xf bank_mask:0xf bound_ctrl:1
	v_add_f32_e32 v30, v30, v31
	ds_write_b32 v63, v30 offset:6240
	v_add_f32_dpp v28, v28, v28 quad_perm:[2,3,0,1] row_mask:0xf bank_mask:0xf bound_ctrl:1
	v_pk_fma_f32 v[54:55], v[88:89], v[34:35], v[24:25] op_sel:[0,1,0] op_sel_hi:[1,1,1]
	v_pk_fma_f32 v[52:53], v[90:91], v[34:35], v[26:27] op_sel:[0,1,0] op_sel_hi:[1,1,1]
	v_add_f32_dpp v28, v28, v28 row_half_mirror row_mask:0xf bank_mask:0xf bound_ctrl:1
	ds_read_b128 v[72:75], v105 offset:14592
	ds_read_b128 v[68:71], v105 offset:14336
	ds_read_b128 v[76:79], v105 offset:14848
	ds_read_b128 v[64:67], v105 offset:13824
	s_waitcnt lgkmcnt(4)
	v_add_f32_dpp v28, v28, v28 row_mirror row_mask:0xf bank_mask:0xf bound_ctrl:1
	v_pk_fma_f32 v[54:55], v[96:97], v[28:29], v[54:55] op_sel_hi:[1,0,1] neg_lo:[1,0,0] neg_hi:[1,0,0]
	v_pk_fma_f32 v[52:53], v[98:99], v[28:29], v[52:53] op_sel_hi:[1,0,1] neg_lo:[1,0,0] neg_hi:[1,0,0]
	v_pk_mul_f32 v[28:29], v[54:55], v[8:9]
	v_pk_fma_f32 v[28:29], v[52:53], v[10:11], v[28:29]
	v_add_f32_e32 v28, v28, v29
	v_pk_mul_f32 v[30:31], v[86:87], v[52:53]
	v_pk_fma_f32 v[30:31], v[84:85], v[54:55], v[30:31]
	v_add_f32_dpp v28, v28, v28 quad_perm:[1,0,3,2] row_mask:0xf bank_mask:0xf bound_ctrl:1
	v_add_f32_e32 v30, v30, v31
	ds_write_b32 v63, v30 offset:7280
	v_add_f32_dpp v28, v28, v28 quad_perm:[2,3,0,1] row_mask:0xf bank_mask:0xf bound_ctrl:1
	v_pk_fma_f32 v[24:25], v[4:5], v[32:33], v[54:55] op_sel_hi:[1,0,1]
	v_pk_fma_f32 v[26:27], v[6:7], v[32:33], v[52:53] op_sel_hi:[1,0,1]
	v_add_f32_dpp v28, v28, v28 row_half_mirror row_mask:0xf bank_mask:0xf bound_ctrl:1
	ds_read_b128 v[92:95], v105 offset:16128
	ds_read_b128 v[88:91], v105 offset:15872
	ds_read_b128 v[96:99], v105 offset:16384
	ds_read_b128 v[84:87], v105 offset:15360
	ds_read2st64_b32 v[34:35], v107 offset0:65 offset1:71
	s_waitcnt lgkmcnt(5)
; __device__ __forceinline__ float allreduce16(float x) { x += dppf<0xB1>(x); x += dppf<0x4E>(x); x += dppf<0x141>(x); x += dppf<0x140>(x); return x; }
; template <int MODE>
; __device__ __forceinline__ void rwkv_scan_unit(int wid_s, const bf16* SIbh_, bf16* Yb_, int ystride, int quarter, float* ldsf) {
;     ...
;                 for (int s = 0; s < 16; ++s) {
;                     const float* qn = B + ((MODE & 2) ? 0 : ((s + 1) & 15)) * 384;
;                     const f32x4 nr4 = *(const f32x4*)(qn + c4), nom4 = *(const f32x4*)(qn + 64 + c4), nk4 = *(const f32x4*)(qn + 128 + c4), nkk4 = *(const f32x4*)(qn + 192 + c4), nka4 = *(const f32x4*)(qn + 256 + c4);
;                     const float nv = qn[320 + rowl];
;                     const f32x2 pa = Sa * (f32x2){kk4.x, kk4.y} + Sb * (f32x2){kk4.z, kk4.w};
;                     const float sa = (MODE & 1) ? (pa.x + pa.y) : allreduce16(pa.x + pa.y);
;                     Sa = Sa - Sa * (f32x2){om4.x, om4.y} + (f32x2){k4.x, k4.y} * v; Sb = Sb - Sb * (f32x2){om4.z, om4.w} + (f32x2){k4.z, k4.w} * v;
;                     Sa = Sa - (f32x2){ka4.x, ka4.y} * sa; Sb = Sb - (f32x2){ka4.z, ka4.w} * sa;
;                     const f32x2 py = Sa * (f32x2){r4.x, r4.y} + Sb * (f32x2){r4.z, r4.w};
;                     PY[s * 260] = py.x + py.y;
;                     r4 = nr4; om4 = nom4; k4 = nk4; kk4 = nkk4; ka4 = nka4; v = nv;
;                 }
	v_add_f32_dpp v28, v28, v28 row_mirror row_mask:0xf bank_mask:0xf bound_ctrl:1
	v_pk_fma_f32 v[24:25], v[12:13], v[28:29], v[24:25] op_sel_hi:[1,0,1] neg_lo:[1,0,0] neg_hi:[1,0,0]
	v_pk_fma_f32 v[26:27], v[14:15], v[28:29], v[26:27] op_sel_hi:[1,0,1] neg_lo:[1,0,0] neg_hi:[1,0,0]
	v_pk_mul_f32 v[28:29], v[24:25], v[72:73]
	v_pk_fma_f32 v[28:29], v[26:27], v[74:75], v[28:29]
	v_add_f32_e32 v28, v28, v29
	v_pk_mul_f32 v[30:31], v[2:3], v[26:27]
	v_pk_fma_f32 v[30:31], v[0:1], v[24:25], v[30:31]
	v_add_f32_dpp v28, v28, v28 quad_perm:[1,0,3,2] row_mask:0xf bank_mask:0xf bound_ctrl:1
	v_add_f32_e32 v30, v30, v31
	ds_write_b32 v63, v30 offset:8320
	v_add_f32_dpp v28, v28, v28 quad_perm:[2,3,0,1] row_mask:0xf bank_mask:0xf bound_ctrl:1
	v_pk_fma_f32 v[54:55], v[68:69], v[32:33], v[24:25] op_sel:[0,1,0] op_sel_hi:[1,1,1]
	v_pk_fma_f32 v[52:53], v[70:71], v[32:33], v[26:27] op_sel:[0,1,0] op_sel_hi:[1,1,1]
	v_add_f32_dpp v28, v28, v28 row_half_mirror row_mask:0xf bank_mask:0xf bound_ctrl:1
	ds_read_b128 v[8:11], v105 offset:17664
	ds_read_b128 v[4:7], v105 offset:17408
	ds_read_b128 v[12:15], v105 offset:17920
	ds_read_b128 v[0:3], v105 offset:16896
	s_waitcnt lgkmcnt(4)
	v_add_f32_dpp v28, v28, v28 row_mirror row_mask:0xf bank_mask:0xf bound_ctrl:1
	v_pk_fma_f32 v[54:55], v[76:77], v[28:29], v[54:55] op_sel_hi:[1,0,1] neg_lo:[1,0,0] neg_hi:[1,0,0]
	v_pk_fma_f32 v[52:53], v[78:79], v[28:29], v[52:53] op_sel_hi:[1,0,1] neg_lo:[1,0,0] neg_hi:[1,0,0]
	v_pk_mul_f32 v[28:29], v[54:55], v[92:93]
	v_pk_fma_f32 v[28:29], v[52:53], v[94:95], v[28:29]
	v_add_f32_e32 v28, v28, v29
	v_pk_mul_f32 v[30:31], v[66:67], v[52:53]
	v_pk_fma_f32 v[30:31], v[64:65], v[54:55], v[30:31]
	v_add_f32_dpp v28, v28, v28 quad_perm:[1,0,3,2] row_mask:0xf bank_mask:0xf bound_ctrl:1
	v_add_f32_e32 v30, v30, v31
	ds_write_b32 v63, v30 offset:9360
	v_add_f32_dpp v28, v28, v28 quad_perm:[2,3,0,1] row_mask:0xf bank_mask:0xf bound_ctrl:1
	v_pk_fma_f32 v[24:25], v[88:89], v[34:35], v[54:55] op_sel_hi:[1,0,1]
	v_pk_fma_f32 v[26:27], v[90:91], v[34:35], v[52:53] op_sel_hi:[1,0,1]
	v_add_f32_dpp v28, v28, v28 row_half_mirror row_mask:0xf bank_mask:0xf bound_ctrl:1
	ds_read_b128 v[72:75], v105 offset:19200
	ds_read_b128 v[68:71], v105 offset:18944
	ds_read_b128 v[76:79], v105 offset:19456
	ds_read_b128 v[64:67], v105 offset:18432
	ds_read2st64_b32 v[32:33], v107 offset0:77 offset1:83
	s_waitcnt lgkmcnt(5)
	v_add_f32_dpp v28, v28, v28 row_mirror row_mask:0xf bank_mask:0xf bound_ctrl:1
	v_pk_fma_f32 v[24:25], v[96:97], v[28:29], v[24:25] op_sel_hi:[1,0,1] neg_lo:[1,0,0] neg_hi:[1,0,0]
	v_pk_fma_f32 v[26:27], v[98:99], v[28:29], v[26:27] op_sel_hi:[1,0,1] neg_lo:[1,0,0] neg_hi:[1,0,0]
	v_pk_mul_f32 v[28:29], v[24:25], v[8:9]
	v_pk_fma_f32 v[28:29], v[26:27], v[10:11], v[28:29]
	v_add_f32_e32 v28, v28, v29
	v_pk_mul_f32 v[30:31], v[86:87], v[26:27]
	v_pk_fma_f32 v[30:31], v[84:85], v[24:25], v[30:31]
	v_add_f32_dpp v28, v28, v28 quad_perm:[1,0,3,2] row_mask:0xf bank_mask:0xf bound_ctrl:1
	v_add_f32_e32 v30, v30, v31
	ds_write_b32 v63, v30 offset:10400
	v_add_f32_dpp v28, v28, v28 quad_perm:[2,3,0,1] row_mask:0xf bank_mask:0xf bound_ctrl:1
	v_pk_fma_f32 v[54:55], v[4:5], v[34:35], v[24:25] op_sel:[0,1,0] op_sel_hi:[1,1,1]
	v_pk_fma_f32 v[52:53], v[6:7], v[34:35], v[26:27] op_sel:[0,1,0] op_sel_hi:[1,1,1]
	v_add_f32_dpp v28, v28, v28 row_half_mirror row_mask:0xf bank_mask:0xf bound_ctrl:1
	ds_read_b128 v[92:95], v105 offset:20736
	ds_read_b128 v[88:91], v105 offset:20480
	ds_read_b128 v[96:99], v105 offset:20992
	ds_read_b128 v[84:87], v105 offset:19968
	s_waitcnt lgkmcnt(4)
	v_add_f32_dpp v28, v28, v28 row_mirror row_mask:0xf bank_mask:0xf bound_ctrl:1
	v_pk_fma_f32 v[54:55], v[12:13], v[28:29], v[54:55] op_sel_hi:[1,0,1] neg_lo:[1,0,0] neg_hi:[1,0,0]
	v_pk_fma_f32 v[52:53], v[14:15], v[28:29], v[52:53] op_sel_hi:[1,0,1] neg_lo:[1,0,0] neg_hi:[1,0,0]
	v_pk_mul_f32 v[28:29], v[54:55], v[72:73]
	v_pk_fma_f32 v[28:29], v[52:53], v[74:75], v[28:29]
	v_add_f32_e32 v28, v28, v29
	v_pk_mul_f32 v[30:31], v[2:3], v[52:53]
	v_pk_fma_f32 v[30:31], v[0:1], v[54:55], v[30:31]
	v_add_f32_dpp v28, v28, v28 quad_perm:[1,0,3,2] row_mask:0xf bank_mask:0xf bound_ctrl:1
	v_add_f32_e32 v30, v30, v31
	ds_write_b32 v63, v30 offset:11440
	v_add_f32_dpp v28, v28, v28 quad_perm:[2,3,0,1] row_mask:0xf bank_mask:0xf bound_ctrl:1
	v_pk_fma_f32 v[24:25], v[68:69], v[32:33], v[54:55] op_sel_hi:[1,0,1]
	v_pk_fma_f32 v[26:27], v[70:71], v[32:33], v[52:53] op_sel_hi:[1,0,1]
	v_add_f32_dpp v28, v28, v28 row_half_mirror row_mask:0xf bank_mask:0xf bound_ctrl:1
	ds_read_b128 v[8:11], v105 offset:22272
	ds_read_b128 v[4:7], v105 offset:22016
	ds_read_b128 v[12:15], v105 offset:22528
	ds_read_b128 v[0:3], v105 offset:21504
	ds_read2st64_b32 v[34:35], v107 offset0:89 offset1:95
	s_waitcnt lgkmcnt(5)
; __device__ __forceinline__ float allreduce16(float x) { x += dppf<0xB1>(x); x += dppf<0x4E>(x); x += dppf<0x141>(x); x += dppf<0x140>(x); return x; }
; template <int MODE>
; __device__ __forceinline__ void rwkv_scan_unit(int wid_s, const bf16* SIbh_, bf16* Yb_, int ystride, int quarter, float* ldsf) {
;     ...
;                 for (int s = 0; s < 16; ++s) {
;                     const float* qn = B + ((MODE & 2) ? 0 : ((s + 1) & 15)) * 384;
;                     const f32x4 nr4 = *(const f32x4*)(qn + c4), nom4 = *(const f32x4*)(qn + 64 + c4), nk4 = *(const f32x4*)(qn + 128 + c4), nkk4 = *(const f32x4*)(qn + 192 + c4), nka4 = *(const f32x4*)(qn + 256 + c4);
;                     const float nv = qn[320 + rowl];
;                     const f32x2 pa = Sa * (f32x2){kk4.x, kk4.y} + Sb * (f32x2){kk4.z, kk4.w};
;                     const float sa = (MODE & 1) ? (pa.x + pa.y) : allreduce16(pa.x + pa.y);
;                     Sa = Sa - Sa * (f32x2){om4.x, om4.y} + (f32x2){k4.x, k4.y} * v; Sb = Sb - Sb * (f32x2){om4.z, om4.w} + (f32x2){k4.z, k4.w} * v;
;                     Sa = Sa - (f32x2){ka4.x, ka4.y} * sa; Sb = Sb - (f32x2){ka4.z, ka4.w} * sa;
;                     const f32x2 py = Sa * (f32x2){r4.x, r4.y} + Sb * (f32x2){r4.z, r4.w};
;                     PY[s * 260] = py.x + py.y;
;                     r4 = nr4; om4 = nom4; k4 = nk4; kk4 = nkk4; ka4 = nka4; v = nv;
;                 }
;                 __builtin_amdgcn_s_setprio(0);
	v_add_f32_dpp v28, v28, v28 row_mirror row_mask:0xf bank_mask:0xf bound_ctrl:1
	v_pk_fma_f32 v[24:25], v[76:77], v[28:29], v[24:25] op_sel_hi:[1,0,1] neg_lo:[1,0,0] neg_hi:[1,0,0]
	v_pk_fma_f32 v[26:27], v[78:79], v[28:29], v[26:27] op_sel_hi:[1,0,1] neg_lo:[1,0,0] neg_hi:[1,0,0]
	v_pk_mul_f32 v[28:29], v[24:25], v[92:93]
	v_pk_fma_f32 v[28:29], v[26:27], v[94:95], v[28:29]
	v_add_f32_e32 v28, v28, v29
	v_pk_mul_f32 v[30:31], v[66:67], v[26:27]
	v_pk_fma_f32 v[30:31], v[64:65], v[24:25], v[30:31]
	v_add_f32_dpp v28, v28, v28 quad_perm:[1,0,3,2] row_mask:0xf bank_mask:0xf bound_ctrl:1
	v_add_f32_e32 v30, v30, v31
	ds_write_b32 v63, v30 offset:12480
	v_add_f32_dpp v28, v28, v28 quad_perm:[2,3,0,1] row_mask:0xf bank_mask:0xf bound_ctrl:1
	v_pk_fma_f32 v[54:55], v[88:89], v[32:33], v[24:25] op_sel:[0,1,0] op_sel_hi:[1,1,1]
	v_pk_fma_f32 v[52:53], v[90:91], v[32:33], v[26:27] op_sel:[0,1,0] op_sel_hi:[1,1,1]
	v_add_f32_dpp v28, v28, v28 row_half_mirror row_mask:0xf bank_mask:0xf bound_ctrl:1
	ds_read_b128 v[72:75], v105 offset:23808
	ds_read_b128 v[68:71], v105 offset:23552
	ds_read_b128 v[76:79], v105 offset:24064
	ds_read_b128 v[64:67], v105 offset:23040
	ds_read_b128 v[36:39], v105 offset:23296
	s_waitcnt lgkmcnt(5)
	v_add_f32_dpp v28, v28, v28 row_mirror row_mask:0xf bank_mask:0xf bound_ctrl:1
	v_pk_fma_f32 v[54:55], v[96:97], v[28:29], v[54:55] op_sel_hi:[1,0,1] neg_lo:[1,0,0] neg_hi:[1,0,0]
	v_pk_fma_f32 v[52:53], v[98:99], v[28:29], v[52:53] op_sel_hi:[1,0,1] neg_lo:[1,0,0] neg_hi:[1,0,0]
	v_pk_mul_f32 v[28:29], v[54:55], v[8:9]
	v_pk_fma_f32 v[28:29], v[52:53], v[10:11], v[28:29]
	v_add_f32_e32 v28, v28, v29
	v_pk_mul_f32 v[30:31], v[86:87], v[52:53]
	v_pk_fma_f32 v[30:31], v[84:85], v[54:55], v[30:31]
	v_add_f32_dpp v28, v28, v28 quad_perm:[1,0,3,2] row_mask:0xf bank_mask:0xf bound_ctrl:1
	v_add_f32_e32 v30, v30, v31
	ds_write_b32 v63, v30 offset:13520
	v_add_f32_dpp v28, v28, v28 quad_perm:[2,3,0,1] row_mask:0xf bank_mask:0xf bound_ctrl:1
	v_pk_fma_f32 v[24:25], v[4:5], v[34:35], v[54:55] op_sel_hi:[1,0,1]
	v_pk_fma_f32 v[26:27], v[6:7], v[34:35], v[52:53] op_sel_hi:[1,0,1]
	v_add_f32_dpp v28, v28, v28 row_half_mirror row_mask:0xf bank_mask:0xf bound_ctrl:1
	s_waitcnt lgkmcnt(0)
	s_nop 0
	v_add_f32_dpp v28, v28, v28 row_mirror row_mask:0xf bank_mask:0xf bound_ctrl:1
	v_pk_fma_f32 v[24:25], v[12:13], v[28:29], v[24:25] op_sel_hi:[1,0,1] neg_lo:[1,0,0] neg_hi:[1,0,0]
	v_pk_fma_f32 v[26:27], v[14:15], v[28:29], v[26:27] op_sel_hi:[1,0,1] neg_lo:[1,0,0] neg_hi:[1,0,0]
	v_pk_mul_f32 v[28:29], v[24:25], v[72:73]
	v_pk_fma_f32 v[28:29], v[26:27], v[74:75], v[28:29]
	v_add_f32_e32 v28, v28, v29
	v_pk_mul_f32 v[30:31], v[2:3], v[26:27]
	v_pk_fma_f32 v[30:31], v[0:1], v[24:25], v[30:31]
	v_add_f32_dpp v28, v28, v28 quad_perm:[1,0,3,2] row_mask:0xf bank_mask:0xf bound_ctrl:1
	v_add_f32_e32 v30, v30, v31
	ds_write_b32 v63, v30 offset:14560
	v_add_f32_dpp v28, v28, v28 quad_perm:[2,3,0,1] row_mask:0xf bank_mask:0xf bound_ctrl:1
	v_pk_fma_f32 v[54:55], v[68:69], v[34:35], v[24:25] op_sel:[0,1,0] op_sel_hi:[1,1,1]
	v_pk_fma_f32 v[52:53], v[70:71], v[34:35], v[26:27] op_sel:[0,1,0] op_sel_hi:[1,1,1]
	v_add_f32_dpp v28, v28, v28 row_half_mirror row_mask:0xf bank_mask:0xf bound_ctrl:1
	s_waitcnt lgkmcnt(0)
	s_nop 0
	v_add_f32_dpp v28, v28, v28 row_mirror row_mask:0xf bank_mask:0xf bound_ctrl:1
	v_pk_fma_f32 v[54:55], v[76:77], v[28:29], v[54:55] op_sel_hi:[1,0,1] neg_lo:[1,0,0] neg_hi:[1,0,0]
	v_pk_fma_f32 v[52:53], v[78:79], v[28:29], v[52:53] op_sel_hi:[1,0,1] neg_lo:[1,0,0] neg_hi:[1,0,0]
	v_pk_mul_f32 v[30:31], v[66:67], v[52:53]
	v_pk_fma_f32 v[30:31], v[64:65], v[54:55], v[30:31]
	v_pk_mul_f32 v[54:55], v[54:55], v[36:37]
	v_pk_mul_f32 v[52:53], v[52:53], v[38:39]
	v_add_f32_e32 v30, v30, v31
	ds_write_b32 v63, v30 offset:15600
	s_setprio 0
	s_branch .LBB0_1401
